# fused cross-attention: packed-f32 softmax + output staged through LDS for full-line 16-byte stores
# baseline (speedup 1.0000x reference)
.LBB0_318:
	s_or_b64 exec, exec, s[6:7]
	s_lshl_b32 s6, s52, 7
	s_add_u32 s6, s71, s6
	s_waitcnt lgkmcnt(0)
	s_barrier
	s_addc_u32 s7, s72, 0
	v_lshlrev_b32_e32 v1, 5, v144
	global_load_dwordx4 v[136:139], v1, s[6:7] offset:16
	global_load_dwordx4 v[144:147], v1, s[6:7]
	s_waitcnt lgkmcnt(0)
	global_load_dwordx4 v[132:135], v1, s[6:7] offset:528
	global_load_dwordx4 v[140:143], v1, s[6:7] offset:512
	s_lshl_b32 s6, s55, 10
	s_add_i32 s6, s6, 0
	v_lshl_add_u32 v3, v3, 4, s6
	v_add_u32_e32 v1, 0x20000, v3
	ds_read_b128 v[154:157], v1
	s_lshl_b32 s8, s52, 6
	s_add_i32 s15, s8, 0
	s_movk_i32 s16, 0x210
	s_ashr_i32 s6, s54, 3
	s_waitcnt lgkmcnt(0)
	v_mov_b32_e32 v158, v155
	v_mov_b32_e32 v159, v156
	v_mov_b32_e32 v155, v157
	v_pk_add_f32 v[154:155], v[158:159], v[154:155]
	v_readlane_b32 s10, v254, 18
	v_add_f32_e32 v1, v154, v155
	v_fmamk_f32 v1, v1, 0x3b800000, v213
	v_rsq_f32_e32 v1, v1
	v_readlane_b32 s11, v254, 19
	v_readlane_b32 s48, v254, 41
	v_readlane_b32 s49, v254, 42
	v_mul_f32_e32 v160, v0, v1
	v_add_u32_e32 v0, 0x20100, v3
	ds_read_b128 v[154:157], v0
	v_pk_mul_f32 v[128:129], v[128:129], v[160:161] op_sel_hi:[1,0]
	v_pk_mul_f32 v[120:121], v[120:121], v[160:161] op_sel_hi:[1,0]
	v_pk_mul_f32 v[124:125], v[124:125], v[160:161] op_sel_hi:[1,0]
	v_pk_mul_f32 v[126:127], v[126:127], v[160:161] op_sel_hi:[1,0]
	s_waitcnt lgkmcnt(0)
	v_mov_b32_e32 v0, v155
	v_mov_b32_e32 v1, v156
	v_mov_b32_e32 v155, v157
	v_pk_add_f32 v[0:1], v[0:1], v[154:155]
	v_pk_mul_f32 v[116:117], v[116:117], v[160:161] op_sel_hi:[1,0]
	v_add_f32_e32 v0, v0, v1
	v_fmamk_f32 v0, v0, 0x3b800000, v213
	v_rsq_f32_e32 v0, v0
	v_pk_mul_f32 v[118:119], v[118:119], v[160:161] op_sel_hi:[1,0]
	v_pk_mul_f32 v[130:131], v[130:131], v[160:161] op_sel_hi:[1,0]
	v_pk_mul_f32 v[122:123], v[122:123], v[160:161] op_sel_hi:[1,0]
	v_mul_f32_e32 v158, v148, v0
	v_add_u32_e32 v0, 0x20200, v3
	ds_read_b128 v[154:157], v0
	v_pk_mul_f32 v[112:113], v[112:113], v[158:159] op_sel_hi:[1,0]
	v_pk_mul_f32 v[100:101], v[100:101], v[158:159] op_sel_hi:[1,0]
	v_pk_mul_f32 v[108:109], v[108:109], v[158:159] op_sel_hi:[1,0]
	v_pk_mul_f32 v[110:111], v[110:111], v[158:159] op_sel_hi:[1,0]
	s_waitcnt lgkmcnt(0)
	v_mov_b32_e32 v0, v155
	v_mov_b32_e32 v1, v156
	v_mov_b32_e32 v155, v157
	v_pk_add_f32 v[0:1], v[0:1], v[154:155]
	v_pk_mul_f32 v[92:93], v[92:93], v[158:159] op_sel_hi:[1,0]
	v_add_f32_e32 v0, v0, v1
	v_fmamk_f32 v0, v0, 0x3b800000, v213
	v_rsq_f32_e32 v0, v0
	v_pk_mul_f32 v[94:95], v[94:95], v[158:159] op_sel_hi:[1,0]
	v_pk_mul_f32 v[102:103], v[102:103], v[158:159] op_sel_hi:[1,0]
	v_pk_mul_f32 v[114:115], v[114:115], v[158:159] op_sel_hi:[1,0]
	v_mul_f32_e32 v156, v150, v0
	v_add_u32_e32 v0, 0x20300, v3
	ds_read_b128 v[174:177], v0
	v_pk_mul_f32 v[84:85], v[84:85], v[156:157] op_sel_hi:[1,0]
	v_pk_mul_f32 v[96:97], v[96:97], v[156:157] op_sel_hi:[1,0]
	v_pk_mul_f32 v[98:99], v[98:99], v[156:157] op_sel_hi:[1,0]
	v_pk_mul_f32 v[76:77], v[76:77], v[156:157] op_sel_hi:[1,0]
	s_waitcnt lgkmcnt(0)
	v_mov_b32_e32 v0, v175
	v_mov_b32_e32 v1, v176
	v_mov_b32_e32 v175, v177
	v_pk_add_f32 v[0:1], v[0:1], v[174:175]
	v_pk_mul_f32 v[78:79], v[78:79], v[156:157] op_sel_hi:[1,0]
	v_add_f32_e32 v0, v0, v1
	v_fmamk_f32 v0, v0, 0x3b800000, v213
	v_rsq_f32_e32 v0, v0
	v_pk_mul_f32 v[86:87], v[86:87], v[156:157] op_sel_hi:[1,0]
	v_mul_f32_e32 v154, v152, v0
	v_add_u32_e32 v0, 0x20800, v3
	ds_read_b128 v[174:177], v0
	s_waitcnt vmcnt(0)
	v_pk_mul_f32 v[128:129], v[144:145], v[128:129]
	v_pk_mul_f32 v[112:113], v[144:145], v[112:113]
	v_pk_mul_f32 v[120:121], v[140:141], v[120:121]
	v_pk_mul_f32 v[100:101], v[140:141], v[100:101]
	s_waitcnt lgkmcnt(0)
	v_mov_b32_e32 v0, v175
	v_mov_b32_e32 v1, v176
	v_mov_b32_e32 v175, v177
	v_pk_add_f32 v[0:1], v[0:1], v[174:175]
	v_pk_mul_f32 v[84:85], v[140:141], v[84:85]
	v_add_f32_e32 v0, v0, v1
	v_fmamk_f32 v0, v0, 0x3b800000, v213
	v_rsq_f32_e32 v0, v0
	v_pk_mul_f32 v[72:73], v[72:73], v[154:155] op_sel_hi:[1,0]
	v_pk_mul_f32 v[80:81], v[80:81], v[154:155] op_sel_hi:[1,0]
	v_pk_mul_f32 v[82:83], v[82:83], v[154:155] op_sel_hi:[1,0]
	v_mul_f32_e32 v152, v162, v0
	v_add_u32_e32 v0, 0x20900, v3
	ds_read_b128 v[174:177], v0
	v_pk_mul_f32 v[72:73], v[140:141], v[72:73]
	v_pk_mul_f32 v[68:69], v[68:69], v[154:155] op_sel_hi:[1,0]
	v_pk_mul_f32 v[70:71], v[70:71], v[154:155] op_sel_hi:[1,0]
	v_pk_mul_f32 v[102:103], v[142:143], v[102:103]
	s_waitcnt lgkmcnt(0)
	v_mov_b32_e32 v0, v175
	v_mov_b32_e32 v1, v176
	v_mov_b32_e32 v175, v177
	v_pk_add_f32 v[0:1], v[0:1], v[174:175]
	v_pk_mul_f32 v[86:87], v[142:143], v[86:87]
	v_add_f32_e32 v0, v0, v1
	v_fmamk_f32 v0, v0, 0x3b800000, v213
	v_rsq_f32_e32 v0, v0
	v_pk_mul_f32 v[130:131], v[146:147], v[130:131]
	v_pk_mul_f32 v[74:75], v[74:75], v[154:155] op_sel_hi:[1,0]
	v_pk_mul_f32 v[122:123], v[142:143], v[122:123]
	v_mul_f32_e32 v150, v164, v0
	v_add_u32_e32 v0, 0x20a00, v3
	ds_read_b128 v[162:165], v0
	v_pk_mul_f32 v[56:57], v[56:57], v[150:151] op_sel_hi:[1,0]
	v_pk_mul_f32 v[20:21], v[20:21], v[150:151] op_sel_hi:[1,0]
	v_pk_mul_f32 v[22:23], v[22:23], v[150:151] op_sel_hi:[1,0]
	v_pk_mul_f32 v[56:57], v[136:137], v[56:57]
	s_waitcnt lgkmcnt(0)
	v_mov_b32_e32 v0, v163
	v_mov_b32_e32 v1, v164
	v_mov_b32_e32 v163, v165
	v_pk_add_f32 v[0:1], v[0:1], v[162:163]
	v_pk_mul_f32 v[22:23], v[142:143], v[22:23]
	v_add_f32_e32 v0, v0, v1
	v_fmamk_f32 v0, v0, 0x3b800000, v213
	v_rsq_f32_e32 v0, v0
	v_pk_mul_f32 v[20:21], v[140:141], v[20:21]
	v_pk_mul_f32 v[16:17], v[16:17], v[150:151] op_sel_hi:[1,0]
	v_pk_mul_f32 v[18:19], v[18:19], v[150:151] op_sel_hi:[1,0]
	v_mul_f32_e32 v148, v166, v0
	v_add_u32_e32 v0, 0x20b00, v3
	ds_read_b128 v[162:165], v0
	v_mov_b32_e32 v3, v217
	v_pk_mul_f32 v[48:49], v[48:49], v[148:149] op_sel_hi:[1,0]
	v_and_b32_e32 v153, 48, v3
	s_waitcnt lgkmcnt(0)
	v_mov_b32_e32 v0, v163
	v_mov_b32_e32 v1, v164
	v_mov_b32_e32 v163, v165
	v_pk_add_f32 v[0:1], v[0:1], v[162:163]
	v_pk_mul_f32 v[162:163], v[138:139], v[126:127]
	v_pk_mul_f32 v[126:127], v[136:137], v[124:125]
	v_cvt_pk_bf16_f32 v124, v128, v129
	v_pk_mul_f32 v[128:129], v[134:135], v[118:119]
	v_pk_mul_f32 v[118:119], v[132:133], v[116:117]
	v_cvt_pk_bf16_f32 v116, v120, v121
	v_pk_mul_f32 v[120:121], v[138:139], v[110:111]
	v_pk_mul_f32 v[110:111], v[136:137], v[108:109]
	v_cvt_pk_bf16_f32 v108, v112, v113
	v_pk_mul_f32 v[112:113], v[134:135], v[94:95]
	v_pk_mul_f32 v[94:95], v[132:133], v[92:93]
	v_cvt_pk_bf16_f32 v92, v100, v101
	v_pk_mul_f32 v[100:101], v[104:105], v[156:157] op_sel_hi:[1,0]
	v_add_f32_e32 v0, v0, v1
	v_pk_mul_f32 v[100:101], v[144:145], v[100:101]
	v_fmamk_f32 v0, v0, 0x3b800000, v213
	v_pk_mul_f32 v[104:105], v[138:139], v[98:99]
	v_pk_mul_f32 v[98:99], v[136:137], v[96:97]
	v_cvt_pk_bf16_f32 v96, v100, v101
	v_pk_mul_f32 v[100:101], v[134:135], v[78:79]
	v_pk_mul_f32 v[78:79], v[132:133], v[76:77]
	v_cvt_pk_bf16_f32 v76, v84, v85
	v_pk_mul_f32 v[84:85], v[88:89], v[154:155] op_sel_hi:[1,0]
	v_pk_mul_f32 v[64:65], v[64:65], v[152:153] op_sel_hi:[1,0]
	v_pk_mul_f32 v[12:13], v[12:13], v[152:153] op_sel_hi:[1,0]
	v_pk_mul_f32 v[14:15], v[14:15], v[152:153] op_sel_hi:[1,0]
	v_rsq_f32_e32 v0, v0
	v_pk_mul_f32 v[84:85], v[144:145], v[84:85]
	v_pk_mul_f32 v[64:65], v[144:145], v[64:65]
	v_pk_mul_f32 v[4:5], v[4:5], v[152:153] op_sel_hi:[1,0]
	v_pk_mul_f32 v[6:7], v[6:7], v[152:153] op_sel_hi:[1,0]
	v_pk_mul_f32 v[14:15], v[142:143], v[14:15]
	v_pk_mul_f32 v[12:13], v[140:141], v[12:13]
	v_pk_mul_f32 v[8:9], v[8:9], v[152:153] op_sel_hi:[1,0]
	v_pk_mul_f32 v[10:11], v[10:11], v[152:153] op_sel_hi:[1,0]
	v_pk_mul_f32 v[88:89], v[138:139], v[82:83]
	v_pk_mul_f32 v[82:83], v[136:137], v[80:81]
	v_cvt_pk_bf16_f32 v80, v84, v85
	v_pk_mul_f32 v[84:85], v[134:135], v[70:71]
	v_pk_mul_f32 v[70:71], v[132:133], v[68:69]
	v_cvt_pk_bf16_f32 v68, v72, v73
	v_pk_mul_f32 v[72:73], v[138:139], v[6:7]
	v_pk_mul_f32 v[6:7], v[136:137], v[4:5]
	v_cvt_pk_bf16_f32 v4, v64, v65
	v_pk_mul_f32 v[64:65], v[134:135], v[10:11]
	v_pk_mul_f32 v[10:11], v[132:133], v[8:9]
	v_cvt_pk_bf16_f32 v8, v12, v13
	v_cvt_pk_bf16_f32 v9, v14, v15
	v_pk_mul_f32 v[12:13], v[60:61], v[150:151] op_sel_hi:[1,0]
	v_pk_mul_f32 v[14:15], v[62:63], v[150:151] op_sel_hi:[1,0]
	v_pk_mul_f32 v[12:13], v[144:145], v[12:13]
	v_pk_mul_f32 v[14:15], v[146:147], v[14:15]
	v_cvt_pk_bf16_f32 v12, v12, v13
	v_cvt_pk_bf16_f32 v13, v14, v15
	v_cvt_pk_bf16_f32 v14, v56, v57
	v_pk_mul_f32 v[56:57], v[134:135], v[18:19]
	v_pk_mul_f32 v[18:19], v[132:133], v[16:17]
	v_cvt_pk_bf16_f32 v16, v20, v21
	v_cvt_pk_bf16_f32 v17, v22, v23
	v_pk_mul_f32 v[20:21], v[52:53], v[148:149] op_sel_hi:[1,0]
	v_pk_mul_f32 v[22:23], v[54:55], v[148:149] op_sel_hi:[1,0]
	v_pk_mul_f32 v[28:29], v[28:29], v[148:149] op_sel_hi:[1,0]
	v_pk_mul_f32 v[30:31], v[30:31], v[148:149] op_sel_hi:[1,0]
	v_mul_f32_e32 v0, v168, v0
	v_pk_mul_f32 v[22:23], v[146:147], v[22:23]
	v_pk_mul_f32 v[20:21], v[144:145], v[20:21]
	v_pk_mul_f32 v[48:49], v[136:137], v[48:49]
	v_pk_mul_f32 v[30:31], v[142:143], v[30:31]
	v_pk_mul_f32 v[28:29], v[140:141], v[28:29]
	v_pk_mul_f32 v[24:25], v[24:25], v[148:149] op_sel_hi:[1,0]
	v_pk_mul_f32 v[26:27], v[26:27], v[148:149] op_sel_hi:[1,0]
	v_cvt_pk_bf16_f32 v20, v20, v21
	v_cvt_pk_bf16_f32 v21, v22, v23
	v_cvt_pk_bf16_f32 v22, v48, v49
	v_pk_mul_f32 v[48:49], v[134:135], v[26:27]
	v_pk_mul_f32 v[26:27], v[132:133], v[24:25]
	v_cvt_pk_bf16_f32 v24, v28, v29
	v_cvt_pk_bf16_f32 v25, v30, v31
	v_pk_mul_f32 v[28:29], v[44:45], v[0:1] op_sel_hi:[1,0]
	v_pk_mul_f32 v[30:31], v[46:47], v[0:1] op_sel_hi:[1,0]
	v_pk_mul_f32 v[40:41], v[40:41], v[0:1] op_sel_hi:[1,0]
	v_pk_mul_f32 v[42:43], v[42:43], v[0:1] op_sel_hi:[1,0]
	v_pk_mul_f32 v[36:37], v[36:37], v[0:1] op_sel_hi:[1,0]
	v_pk_mul_f32 v[38:39], v[38:39], v[0:1] op_sel_hi:[1,0]
	v_pk_mul_f32 v[32:33], v[32:33], v[0:1] op_sel_hi:[1,0]
	v_pk_mul_f32 v[0:1], v[34:35], v[0:1] op_sel_hi:[1,0]
	v_readfirstlane_b32 s7, v3
	v_pk_mul_f32 v[0:1], v[134:135], v[0:1]
	v_pk_mul_f32 v[34:35], v[132:133], v[32:33]
	s_ashr_i32 s8, s7, 2
	v_pk_mul_f32 v[36:37], v[140:141], v[36:37]
	v_cvt_pk_bf16_f32 v34, v34, v35
	v_cvt_pk_bf16_f32 v35, v0, v1
	v_bfi_b32 v1, -16, s8, v3
	v_cvt_pk_bf16_f32 v32, v36, v37
	v_mul_lo_u32 v36, v1, s16
	v_add3_u32 v175, 0, v36, v153
	v_ashrrev_i32_e32 v36, 3, v3
	v_pk_mul_f32 v[30:31], v[146:147], v[30:31]
	v_pk_mul_f32 v[28:29], v[144:145], v[28:29]
	v_pk_mul_f32 v[40:41], v[136:137], v[40:41]
	v_pk_mul_f32 v[38:39], v[142:143], v[38:39]
	v_ashrrev_i32_e32 v37, 31, v36
	v_cvt_pk_bf16_f32 v28, v28, v29
	v_cvt_pk_bf16_f32 v29, v30, v31
	v_cvt_pk_bf16_f32 v30, v40, v41
	v_cvt_pk_bf16_f32 v33, v38, v39
	v_and_b32_e32 v38, 15, v3
	v_bfe_u32 v39, v3, 4, 2
	v_lshlrev_b64 v[44:45], 13, v[36:37]
	v_lshlrev_b32_e32 v37, 3, v3
	v_lshlrev_b32_e32 v40, 4, v3
	v_bfe_u32 v3, v3, 2, 2
	v_mul_lo_u32 v36, v36, s16
	v_and_b32_e32 v180, 0x70, v40
	v_lshl_or_b32 v3, v39, 2, v3
	s_ashr_i32 s7, s6, 31
	s_lshl_b32 s8, s53, 8
	v_add3_u32 v170, s10, v36, v180
	v_mul_u32_u24_e32 v38, 0x210, v38
	v_add3_u32 v168, s11, v36, v180
	v_mul_u32_u24_e32 v3, 0x210, v3
	v_and_b32_e32 v36, 24, v37
	s_lshl_b64 s[12:13], s[6:7], 21
	s_ashr_i32 s9, s8, 31
	v_add3_u32 v174, s10, v153, v38
	v_add3_u32 v173, s11, v153, v38
	v_add3_u32 v169, s10, v3, v36
	v_add3_u32 v3, s11, v3, v36
	s_lshl_b64 s[10:11], s[6:7], 22
	s_add_u32 s12, s60, s12
	s_addc_u32 s13, s61, s13
	v_lshl_add_u64 v[44:45], s[12:13], 0, v[44:45]
	s_lshl_b32 s12, s0, 11
	s_ashr_i32 s13, s12, 31
	v_cvt_pk_bf16_f32 v93, v102, v103
	v_pk_mul_f32 v[102:103], v[106:107], v[156:157] op_sel_hi:[1,0]
	v_cvt_pk_bf16_f32 v77, v86, v87
	v_pk_mul_f32 v[86:87], v[90:91], v[154:155] op_sel_hi:[1,0]
	v_mul_lo_u32 v36, v149, s16
	v_lshl_add_u64 v[44:45], s[12:13], 1, v[44:45]
	s_lshl_b64 s[8:9], s[8:9], 1
	v_cvt_pk_bf16_f32 v125, v130, v131
	v_cvt_pk_bf16_f32 v126, v126, v127
	v_cvt_pk_bf16_f32 v127, v162, v163
	v_pk_mul_f32 v[114:115], v[146:147], v[114:115]
	v_pk_mul_f32 v[102:103], v[146:147], v[102:103]
	v_pk_mul_f32 v[86:87], v[146:147], v[86:87]
	v_pk_mul_f32 v[74:75], v[142:143], v[74:75]
	v_add3_u32 v176, s15, v151, v36
	v_lshl_add_u64 v[44:45], v[44:45], 0, s[8:9]
	v_cvt_pk_bf16_f32 v117, v122, v123
	v_cvt_pk_bf16_f32 v118, v118, v119
	v_cvt_pk_bf16_f32 v119, v128, v129
	v_cvt_pk_bf16_f32 v109, v114, v115
	v_cvt_pk_bf16_f32 v110, v110, v111
	v_cvt_pk_bf16_f32 v111, v120, v121
	v_cvt_pk_bf16_f32 v94, v94, v95
	v_cvt_pk_bf16_f32 v95, v112, v113
	v_cvt_pk_bf16_f32 v97, v102, v103
	v_cvt_pk_bf16_f32 v98, v98, v99
	v_cvt_pk_bf16_f32 v99, v104, v105
	v_cvt_pk_bf16_f32 v78, v78, v79
	v_cvt_pk_bf16_f32 v79, v100, v101
	v_cvt_pk_bf16_f32 v81, v86, v87
	v_cvt_pk_bf16_f32 v82, v82, v83
	v_cvt_pk_bf16_f32 v83, v88, v89
	v_cvt_pk_bf16_f32 v69, v74, v75
	v_cvt_pk_bf16_f32 v70, v70, v71
	v_cvt_pk_bf16_f32 v71, v84, v85
	s_waitcnt lgkmcnt(0)
	v_pk_mul_f32 v[66:67], v[66:67], v[152:153] op_sel_hi:[1,0]
	v_pk_mul_f32 v[58:59], v[58:59], v[150:151] op_sel_hi:[1,0]
	v_pk_mul_f32 v[50:51], v[50:51], v[148:149] op_sel_hi:[1,0]
	v_pk_mul_f32 v[42:43], v[138:139], v[42:43]
	v_pk_mul_f32 v[66:67], v[146:147], v[66:67]
	v_pk_mul_f32 v[58:59], v[138:139], v[58:59]
	v_pk_mul_f32 v[50:51], v[138:139], v[50:51]
	v_cvt_pk_bf16_f32 v31, v42, v43
	v_cvt_pk_bf16_f32 v5, v66, v67
	v_cvt_pk_bf16_f32 v6, v6, v7
	v_cvt_pk_bf16_f32 v7, v72, v73
	v_cvt_pk_bf16_f32 v10, v10, v11
	v_cvt_pk_bf16_f32 v11, v64, v65
	v_cvt_pk_bf16_f32 v15, v58, v59
	v_cvt_pk_bf16_f32 v18, v18, v19
	v_cvt_pk_bf16_f32 v19, v56, v57
	v_cvt_pk_bf16_f32 v23, v50, v51
	v_cvt_pk_bf16_f32 v26, v26, v27
	v_cvt_pk_bf16_f32 v27, v48, v49
	v_lshl_add_u64 v[210:211], v[44:45], 0, v[180:181]
	v_mov_b32_e32 v187, v170
	v_mov_b32_e32 v249, v174
	v_mov_b32_e32 v189, v171
	v_mov_b32_e32 v222, v172
	v_add_u32_e32 v218, 0x10800, v176
	v_add_u32_e32 v219, 0x10800, v175
	v_mov_b32_e32 v180, v169
	global_load_dwordx4 v[236:239], v[210:211], off
	global_load_dwordx4 v[240:243], v[210:211], off offset:128
	global_load_dwordx4 v[164:167], v[210:211], off offset:256
	global_load_dwordx4 v[182:185], v[210:211], off offset:384
	s_barrier
	ds_write_b128 v176, v[124:127]
	ds_write_b128 v176, v[116:119] offset:256
	ds_write_b128 v176, v[108:111] offset:8448
	ds_write_b128 v176, v[92:95] offset:8704
	ds_write_b128 v176, v[96:99] offset:16896
	ds_write_b128 v176, v[76:79] offset:17152
	ds_write_b128 v176, v[80:83] offset:25344
	ds_write_b128 v176, v[68:71] offset:25600
	ds_write_b128 v218, v[4:7]
	ds_write_b128 v218, v[8:11] offset:256
	ds_write_b128 v218, v[12:15] offset:8448
	ds_write_b128 v218, v[16:19] offset:8704
	ds_write_b128 v218, v[20:23] offset:16896
	ds_write_b128 v218, v[24:27] offset:17152
	ds_write_b128 v218, v[28:31] offset:25344
	ds_write_b128 v218, v[32:35] offset:25600
	s_waitcnt lgkmcnt(0)
	s_barrier
	ds_read_b128 v[132:135], v175
	ds_read_b128 v[136:139], v175 offset:64
	ds_read_b128 v[140:143], v175 offset:128
	ds_read_b128 v[144:147], v175 offset:192
	ds_read_b128 v[148:151], v175 offset:256
	ds_read_b128 v[152:155], v175 offset:320
	ds_read_b128 v[156:159], v175 offset:384
	ds_read_b128 v[160:163], v175 offset:448
	ds_read_b128 v[190:193], v219
	ds_read_b128 v[194:197], v219 offset:64
	ds_read_b128 v[198:201], v219 offset:128
	ds_read_b128 v[202:205], v219 offset:192
	ds_read_b128 v[206:209], v219 offset:256
	ds_read_b128 v[224:227], v219 offset:320
	ds_read_b128 v[228:231], v219 offset:384
	ds_read_b128 v[232:235], v219 offset:448
	s_waitcnt lgkmcnt(0)
	s_barrier
	s_waitcnt vmcnt(0)
	ds_write_b128 v187, v[236:239]
	ds_write_b128 v187, v[240:243] offset:128
	ds_write_b128 v187, v[164:167] offset:256
	ds_write_b128 v187, v[182:185] offset:384
	v_add_co_u32_e32 v218, vcc, 0x80000, v210
	s_nop 1
	v_addc_co_u32_e32 v219, vcc, 0, v211, vcc
	global_load_dwordx4 v[236:239], v[218:219], off
	global_load_dwordx4 v[240:243], v[218:219], off offset:128
	global_load_dwordx4 v[164:167], v[218:219], off offset:256
	global_load_dwordx4 v[182:185], v[218:219], off offset:384
	s_waitcnt lgkmcnt(0)
	s_barrier
	ds_read_b128 v[0:3], v249
	ds_read_b128 v[168:171], v249 offset:64
	ds_read_b128 v[172:175], v249 offset:128
	ds_read_b128 v[176:179], v249 offset:192
	s_waitcnt lgkmcnt(3)
	v_mfma_f32_16x16x32_bf16 v[4:7], v[0:3], v[132:135], 0
	v_mfma_f32_16x16x32_bf16 v[68:71], v[0:3], v[190:193], 0
	ds_read_b128 v[0:3], v249 offset:256
	s_waitcnt lgkmcnt(3)
	v_mfma_f32_16x16x32_bf16 v[4:7], v[168:171], v[136:139], v[4:7]
	v_mfma_f32_16x16x32_bf16 v[68:71], v[168:171], v[194:197], v[68:71]
	ds_read_b128 v[168:171], v249 offset:320
	s_waitcnt lgkmcnt(3)
	v_mfma_f32_16x16x32_bf16 v[4:7], v[172:175], v[140:143], v[4:7]
	v_mfma_f32_16x16x32_bf16 v[68:71], v[172:175], v[198:201], v[68:71]
	ds_read_b128 v[172:175], v249 offset:384
	s_waitcnt lgkmcnt(3)
	v_mfma_f32_16x16x32_bf16 v[4:7], v[176:179], v[144:147], v[4:7]
	v_mfma_f32_16x16x32_bf16 v[68:71], v[176:179], v[202:205], v[68:71]
	ds_read_b128 v[176:179], v249 offset:448
	s_waitcnt lgkmcnt(3)
	v_mfma_f32_16x16x32_bf16 v[4:7], v[0:3], v[148:151], v[4:7]
	v_mfma_f32_16x16x32_bf16 v[68:71], v[0:3], v[206:209], v[68:71]
	ds_read_b128 v[0:3], v249 offset:8448
	s_waitcnt lgkmcnt(3)
	v_mfma_f32_16x16x32_bf16 v[4:7], v[168:171], v[152:155], v[4:7]
	v_mfma_f32_16x16x32_bf16 v[68:71], v[168:171], v[224:227], v[68:71]
	ds_read_b128 v[168:171], v249 offset:8512
	s_waitcnt lgkmcnt(3)
	v_mfma_f32_16x16x32_bf16 v[4:7], v[172:175], v[156:159], v[4:7]
	v_mfma_f32_16x16x32_bf16 v[68:71], v[172:175], v[228:231], v[68:71]
	ds_read_b128 v[172:175], v249 offset:8576
	s_waitcnt lgkmcnt(3)
	v_mfma_f32_16x16x32_bf16 v[4:7], v[176:179], v[160:163], v[4:7]
	v_mfma_f32_16x16x32_bf16 v[68:71], v[176:179], v[232:235], v[68:71]
	ds_read_b128 v[176:179], v249 offset:8640
	s_waitcnt lgkmcnt(3)
	v_mfma_f32_16x16x32_bf16 v[8:11], v[0:3], v[132:135], 0
	v_mfma_f32_16x16x32_bf16 v[72:75], v[0:3], v[190:193], 0
	ds_read_b128 v[0:3], v249 offset:8704
	s_waitcnt lgkmcnt(3)
	v_mfma_f32_16x16x32_bf16 v[8:11], v[168:171], v[136:139], v[8:11]
	v_mfma_f32_16x16x32_bf16 v[72:75], v[168:171], v[194:197], v[72:75]
	ds_read_b128 v[168:171], v249 offset:8768
	s_waitcnt lgkmcnt(3)
	v_mfma_f32_16x16x32_bf16 v[8:11], v[172:175], v[140:143], v[8:11]
	v_mfma_f32_16x16x32_bf16 v[72:75], v[172:175], v[198:201], v[72:75]
	ds_read_b128 v[172:175], v249 offset:8832
	s_waitcnt lgkmcnt(3)
	v_mfma_f32_16x16x32_bf16 v[8:11], v[176:179], v[144:147], v[8:11]
	v_mfma_f32_16x16x32_bf16 v[72:75], v[176:179], v[202:205], v[72:75]
	ds_read_b128 v[176:179], v249 offset:8896
	s_waitcnt lgkmcnt(3)
	v_mfma_f32_16x16x32_bf16 v[8:11], v[0:3], v[148:151], v[8:11]
	v_mfma_f32_16x16x32_bf16 v[72:75], v[0:3], v[206:209], v[72:75]
	ds_read_b128 v[0:3], v249 offset:16896
	s_waitcnt lgkmcnt(3)
	v_mfma_f32_16x16x32_bf16 v[8:11], v[168:171], v[152:155], v[8:11]
	v_mfma_f32_16x16x32_bf16 v[72:75], v[168:171], v[224:227], v[72:75]
	ds_read_b128 v[168:171], v249 offset:16960
	s_waitcnt lgkmcnt(3)
	v_mfma_f32_16x16x32_bf16 v[8:11], v[172:175], v[156:159], v[8:11]
	v_mfma_f32_16x16x32_bf16 v[72:75], v[172:175], v[228:231], v[72:75]
	ds_read_b128 v[172:175], v249 offset:17024
	s_waitcnt lgkmcnt(3)
	v_mfma_f32_16x16x32_bf16 v[8:11], v[176:179], v[160:163], v[8:11]
	v_mfma_f32_16x16x32_bf16 v[72:75], v[176:179], v[232:235], v[72:75]
	ds_read_b128 v[176:179], v249 offset:17088
	s_waitcnt lgkmcnt(3)
	v_mfma_f32_16x16x32_bf16 v[12:15], v[0:3], v[132:135], 0
	v_mfma_f32_16x16x32_bf16 v[76:79], v[0:3], v[190:193], 0
	ds_read_b128 v[0:3], v249 offset:17152
	s_waitcnt lgkmcnt(3)
	v_mfma_f32_16x16x32_bf16 v[12:15], v[168:171], v[136:139], v[12:15]
	v_mfma_f32_16x16x32_bf16 v[76:79], v[168:171], v[194:197], v[76:79]
	ds_read_b128 v[168:171], v249 offset:17216
	s_waitcnt lgkmcnt(3)
	v_mfma_f32_16x16x32_bf16 v[12:15], v[172:175], v[140:143], v[12:15]
	v_mfma_f32_16x16x32_bf16 v[76:79], v[172:175], v[198:201], v[76:79]
	ds_read_b128 v[172:175], v249 offset:17280
	s_waitcnt lgkmcnt(3)
	v_mfma_f32_16x16x32_bf16 v[12:15], v[176:179], v[144:147], v[12:15]
	v_mfma_f32_16x16x32_bf16 v[76:79], v[176:179], v[202:205], v[76:79]
	ds_read_b128 v[176:179], v249 offset:17344
	s_waitcnt lgkmcnt(3)
	v_mfma_f32_16x16x32_bf16 v[12:15], v[0:3], v[148:151], v[12:15]
	v_mfma_f32_16x16x32_bf16 v[76:79], v[0:3], v[206:209], v[76:79]
	ds_read_b128 v[0:3], v249 offset:25344
	s_waitcnt lgkmcnt(3)
	v_mfma_f32_16x16x32_bf16 v[12:15], v[168:171], v[152:155], v[12:15]
	v_mfma_f32_16x16x32_bf16 v[76:79], v[168:171], v[224:227], v[76:79]
	ds_read_b128 v[168:171], v249 offset:25408
	s_waitcnt lgkmcnt(3)
	v_mfma_f32_16x16x32_bf16 v[12:15], v[172:175], v[156:159], v[12:15]
	v_mfma_f32_16x16x32_bf16 v[76:79], v[172:175], v[228:231], v[76:79]
	ds_read_b128 v[172:175], v249 offset:25472
	s_waitcnt lgkmcnt(3)
	v_mfma_f32_16x16x32_bf16 v[12:15], v[176:179], v[160:163], v[12:15]
	v_mfma_f32_16x16x32_bf16 v[76:79], v[176:179], v[232:235], v[76:79]
	ds_read_b128 v[176:179], v249 offset:25536
	s_waitcnt lgkmcnt(3)
	v_mfma_f32_16x16x32_bf16 v[16:19], v[0:3], v[132:135], 0
	v_mfma_f32_16x16x32_bf16 v[80:83], v[0:3], v[190:193], 0
	ds_read_b128 v[0:3], v249 offset:25600
	s_waitcnt lgkmcnt(3)
	v_mfma_f32_16x16x32_bf16 v[16:19], v[168:171], v[136:139], v[16:19]
	v_mfma_f32_16x16x32_bf16 v[80:83], v[168:171], v[194:197], v[80:83]
	ds_read_b128 v[168:171], v249 offset:25664
	s_waitcnt lgkmcnt(3)
	v_mfma_f32_16x16x32_bf16 v[16:19], v[172:175], v[140:143], v[16:19]
	v_mfma_f32_16x16x32_bf16 v[80:83], v[172:175], v[198:201], v[80:83]
	ds_read_b128 v[172:175], v249 offset:25728
	s_waitcnt lgkmcnt(3)
	v_mfma_f32_16x16x32_bf16 v[16:19], v[176:179], v[144:147], v[16:19]
	v_mfma_f32_16x16x32_bf16 v[80:83], v[176:179], v[202:205], v[80:83]
	ds_read_b128 v[176:179], v249 offset:25792
	s_waitcnt lgkmcnt(3)
	v_mfma_f32_16x16x32_bf16 v[16:19], v[0:3], v[148:151], v[16:19]
	v_mfma_f32_16x16x32_bf16 v[80:83], v[0:3], v[206:209], v[80:83]
	s_waitcnt lgkmcnt(2)
	v_mfma_f32_16x16x32_bf16 v[16:19], v[168:171], v[152:155], v[16:19]
	v_mfma_f32_16x16x32_bf16 v[80:83], v[168:171], v[224:227], v[80:83]
	s_waitcnt lgkmcnt(1)
	v_mfma_f32_16x16x32_bf16 v[16:19], v[172:175], v[156:159], v[16:19]
	v_mfma_f32_16x16x32_bf16 v[80:83], v[172:175], v[228:231], v[80:83]
	s_waitcnt lgkmcnt(0)
	v_mfma_f32_16x16x32_bf16 v[16:19], v[176:179], v[160:163], v[16:19]
	v_mfma_f32_16x16x32_bf16 v[80:83], v[176:179], v[232:235], v[80:83]
	s_waitcnt vmcnt(0)
	ds_write_b128 v187, v[236:239] offset:33792
	ds_write_b128 v187, v[240:243] offset:33920
	ds_write_b128 v187, v[164:167] offset:34048
	ds_write_b128 v187, v[182:185] offset:34176
	v_add_co_u32_e32 v218, vcc, 0x100000, v210
	s_nop 1
	v_addc_co_u32_e32 v219, vcc, 0, v211, vcc
	global_load_dwordx4 v[236:239], v[218:219], off
	global_load_dwordx4 v[240:243], v[218:219], off offset:128
	global_load_dwordx4 v[164:167], v[218:219], off offset:256
	global_load_dwordx4 v[182:185], v[218:219], off offset:384
	s_waitcnt lgkmcnt(0)
	s_barrier
	ds_read_b128 v[0:3], v249 offset:33792
	ds_read_b128 v[168:171], v249 offset:33856
	ds_read_b128 v[172:175], v249 offset:33920
	ds_read_b128 v[176:179], v249 offset:33984
	s_waitcnt lgkmcnt(3)
	v_mfma_f32_16x16x32_bf16 v[20:23], v[0:3], v[132:135], 0
	v_mfma_f32_16x16x32_bf16 v[84:87], v[0:3], v[190:193], 0
	ds_read_b128 v[0:3], v249 offset:34048
	s_waitcnt lgkmcnt(3)
	v_mfma_f32_16x16x32_bf16 v[20:23], v[168:171], v[136:139], v[20:23]
	v_mfma_f32_16x16x32_bf16 v[84:87], v[168:171], v[194:197], v[84:87]
	ds_read_b128 v[168:171], v249 offset:34112
	s_waitcnt lgkmcnt(3)
	v_mfma_f32_16x16x32_bf16 v[20:23], v[172:175], v[140:143], v[20:23]
	v_mfma_f32_16x16x32_bf16 v[84:87], v[172:175], v[198:201], v[84:87]
	ds_read_b128 v[172:175], v249 offset:34176
	s_waitcnt lgkmcnt(3)
	v_mfma_f32_16x16x32_bf16 v[20:23], v[176:179], v[144:147], v[20:23]
	v_mfma_f32_16x16x32_bf16 v[84:87], v[176:179], v[202:205], v[84:87]
	ds_read_b128 v[176:179], v249 offset:34240
	s_waitcnt lgkmcnt(3)
	v_mfma_f32_16x16x32_bf16 v[20:23], v[0:3], v[148:151], v[20:23]
	v_mfma_f32_16x16x32_bf16 v[84:87], v[0:3], v[206:209], v[84:87]
	ds_read_b128 v[0:3], v249 offset:42240
	s_waitcnt lgkmcnt(3)
	v_mfma_f32_16x16x32_bf16 v[20:23], v[168:171], v[152:155], v[20:23]
	v_mfma_f32_16x16x32_bf16 v[84:87], v[168:171], v[224:227], v[84:87]
	ds_read_b128 v[168:171], v249 offset:42304
	s_waitcnt lgkmcnt(3)
	v_mfma_f32_16x16x32_bf16 v[20:23], v[172:175], v[156:159], v[20:23]
	v_mfma_f32_16x16x32_bf16 v[84:87], v[172:175], v[228:231], v[84:87]
	ds_read_b128 v[172:175], v249 offset:42368
	s_waitcnt lgkmcnt(3)
	v_mfma_f32_16x16x32_bf16 v[20:23], v[176:179], v[160:163], v[20:23]
	v_mfma_f32_16x16x32_bf16 v[84:87], v[176:179], v[232:235], v[84:87]
	ds_read_b128 v[176:179], v249 offset:42432
	s_waitcnt lgkmcnt(3)
	v_mfma_f32_16x16x32_bf16 v[24:27], v[0:3], v[132:135], 0
	v_mfma_f32_16x16x32_bf16 v[88:91], v[0:3], v[190:193], 0
	ds_read_b128 v[0:3], v249 offset:42496
	s_waitcnt lgkmcnt(3)
	v_mfma_f32_16x16x32_bf16 v[24:27], v[168:171], v[136:139], v[24:27]
	v_mfma_f32_16x16x32_bf16 v[88:91], v[168:171], v[194:197], v[88:91]
	ds_read_b128 v[168:171], v249 offset:42560
	s_waitcnt lgkmcnt(3)
	v_mfma_f32_16x16x32_bf16 v[24:27], v[172:175], v[140:143], v[24:27]
	v_mfma_f32_16x16x32_bf16 v[88:91], v[172:175], v[198:201], v[88:91]
	ds_read_b128 v[172:175], v249 offset:42624
	s_waitcnt lgkmcnt(3)
	v_mfma_f32_16x16x32_bf16 v[24:27], v[176:179], v[144:147], v[24:27]
	v_mfma_f32_16x16x32_bf16 v[88:91], v[176:179], v[202:205], v[88:91]
	ds_read_b128 v[176:179], v249 offset:42688
	s_waitcnt lgkmcnt(3)
	v_mfma_f32_16x16x32_bf16 v[24:27], v[0:3], v[148:151], v[24:27]
	v_mfma_f32_16x16x32_bf16 v[88:91], v[0:3], v[206:209], v[88:91]
	ds_read_b128 v[0:3], v249 offset:50688
	s_waitcnt lgkmcnt(3)
	v_mfma_f32_16x16x32_bf16 v[24:27], v[168:171], v[152:155], v[24:27]
	v_mfma_f32_16x16x32_bf16 v[88:91], v[168:171], v[224:227], v[88:91]
	ds_read_b128 v[168:171], v249 offset:50752
	s_waitcnt lgkmcnt(3)
	v_mfma_f32_16x16x32_bf16 v[24:27], v[172:175], v[156:159], v[24:27]
	v_mfma_f32_16x16x32_bf16 v[88:91], v[172:175], v[228:231], v[88:91]
	ds_read_b128 v[172:175], v249 offset:50816
	s_waitcnt lgkmcnt(3)
	v_mfma_f32_16x16x32_bf16 v[24:27], v[176:179], v[160:163], v[24:27]
	v_mfma_f32_16x16x32_bf16 v[88:91], v[176:179], v[232:235], v[88:91]
	ds_read_b128 v[176:179], v249 offset:50880
	s_waitcnt lgkmcnt(3)
	v_mfma_f32_16x16x32_bf16 v[28:31], v[0:3], v[132:135], 0
	v_mfma_f32_16x16x32_bf16 v[92:95], v[0:3], v[190:193], 0
	ds_read_b128 v[0:3], v249 offset:50944
	s_waitcnt lgkmcnt(3)
	v_mfma_f32_16x16x32_bf16 v[28:31], v[168:171], v[136:139], v[28:31]
	v_mfma_f32_16x16x32_bf16 v[92:95], v[168:171], v[194:197], v[92:95]
	ds_read_b128 v[168:171], v249 offset:51008
	s_waitcnt lgkmcnt(3)
	v_mfma_f32_16x16x32_bf16 v[28:31], v[172:175], v[140:143], v[28:31]
	v_mfma_f32_16x16x32_bf16 v[92:95], v[172:175], v[198:201], v[92:95]
	ds_read_b128 v[172:175], v249 offset:51072
	s_waitcnt lgkmcnt(3)
	v_mfma_f32_16x16x32_bf16 v[28:31], v[176:179], v[144:147], v[28:31]
	v_mfma_f32_16x16x32_bf16 v[92:95], v[176:179], v[202:205], v[92:95]
	ds_read_b128 v[176:179], v249 offset:51136
	s_waitcnt lgkmcnt(3)
	v_mfma_f32_16x16x32_bf16 v[28:31], v[0:3], v[148:151], v[28:31]
	v_mfma_f32_16x16x32_bf16 v[92:95], v[0:3], v[206:209], v[92:95]
	ds_read_b128 v[0:3], v249 offset:59136
	s_waitcnt lgkmcnt(3)
	v_mfma_f32_16x16x32_bf16 v[28:31], v[168:171], v[152:155], v[28:31]
	v_mfma_f32_16x16x32_bf16 v[92:95], v[168:171], v[224:227], v[92:95]
	ds_read_b128 v[168:171], v249 offset:59200
	s_waitcnt lgkmcnt(3)
	v_mfma_f32_16x16x32_bf16 v[28:31], v[172:175], v[156:159], v[28:31]
	v_mfma_f32_16x16x32_bf16 v[92:95], v[172:175], v[228:231], v[92:95]
	ds_read_b128 v[172:175], v249 offset:59264
	s_waitcnt lgkmcnt(3)
	v_mfma_f32_16x16x32_bf16 v[28:31], v[176:179], v[160:163], v[28:31]
	v_mfma_f32_16x16x32_bf16 v[92:95], v[176:179], v[232:235], v[92:95]
	ds_read_b128 v[176:179], v249 offset:59328
	s_waitcnt lgkmcnt(3)
	v_mfma_f32_16x16x32_bf16 v[32:35], v[0:3], v[132:135], 0
	v_mfma_f32_16x16x32_bf16 v[96:99], v[0:3], v[190:193], 0
	ds_read_b128 v[0:3], v249 offset:59392
	s_waitcnt lgkmcnt(3)
	v_mfma_f32_16x16x32_bf16 v[32:35], v[168:171], v[136:139], v[32:35]
	v_mfma_f32_16x16x32_bf16 v[96:99], v[168:171], v[194:197], v[96:99]
	ds_read_b128 v[168:171], v249 offset:59456
	s_waitcnt lgkmcnt(3)
	v_mfma_f32_16x16x32_bf16 v[32:35], v[172:175], v[140:143], v[32:35]
	v_mfma_f32_16x16x32_bf16 v[96:99], v[172:175], v[198:201], v[96:99]
	ds_read_b128 v[172:175], v249 offset:59520
	s_waitcnt lgkmcnt(3)
	v_mfma_f32_16x16x32_bf16 v[32:35], v[176:179], v[144:147], v[32:35]
	v_mfma_f32_16x16x32_bf16 v[96:99], v[176:179], v[202:205], v[96:99]
	ds_read_b128 v[176:179], v249 offset:59584
	s_waitcnt lgkmcnt(3)
	v_mfma_f32_16x16x32_bf16 v[32:35], v[0:3], v[148:151], v[32:35]
	v_mfma_f32_16x16x32_bf16 v[96:99], v[0:3], v[206:209], v[96:99]
	s_waitcnt lgkmcnt(2)
	v_mfma_f32_16x16x32_bf16 v[32:35], v[168:171], v[152:155], v[32:35]
	v_mfma_f32_16x16x32_bf16 v[96:99], v[168:171], v[224:227], v[96:99]
	s_waitcnt lgkmcnt(1)
	v_mfma_f32_16x16x32_bf16 v[32:35], v[172:175], v[156:159], v[32:35]
	v_mfma_f32_16x16x32_bf16 v[96:99], v[172:175], v[228:231], v[96:99]
	s_waitcnt lgkmcnt(0)
	v_mfma_f32_16x16x32_bf16 v[32:35], v[176:179], v[160:163], v[32:35]
	v_mfma_f32_16x16x32_bf16 v[96:99], v[176:179], v[232:235], v[96:99]
	s_waitcnt vmcnt(0)
	ds_write_b128 v187, v[236:239]
	ds_write_b128 v187, v[240:243] offset:128
	ds_write_b128 v187, v[164:167] offset:256
	ds_write_b128 v187, v[182:185] offset:384
	v_add_co_u32_e32 v218, vcc, 0x180000, v210
	s_nop 1
	v_addc_co_u32_e32 v219, vcc, 0, v211, vcc
	global_load_dwordx4 v[236:239], v[218:219], off
	global_load_dwordx4 v[240:243], v[218:219], off offset:128
	global_load_dwordx4 v[164:167], v[218:219], off offset:256
	global_load_dwordx4 v[182:185], v[218:219], off offset:384
	s_waitcnt lgkmcnt(0)
	s_barrier
	ds_read_b128 v[0:3], v249
	ds_read_b128 v[168:171], v249 offset:64
	ds_read_b128 v[172:175], v249 offset:128
	ds_read_b128 v[176:179], v249 offset:192
	s_waitcnt lgkmcnt(3)
	v_mfma_f32_16x16x32_bf16 v[36:39], v[0:3], v[132:135], 0
	v_mfma_f32_16x16x32_bf16 v[100:103], v[0:3], v[190:193], 0
	ds_read_b128 v[0:3], v249 offset:256
	s_waitcnt lgkmcnt(3)
	v_mfma_f32_16x16x32_bf16 v[36:39], v[168:171], v[136:139], v[36:39]
	v_mfma_f32_16x16x32_bf16 v[100:103], v[168:171], v[194:197], v[100:103]
	ds_read_b128 v[168:171], v249 offset:320
	s_waitcnt lgkmcnt(3)
	v_mfma_f32_16x16x32_bf16 v[36:39], v[172:175], v[140:143], v[36:39]
	v_mfma_f32_16x16x32_bf16 v[100:103], v[172:175], v[198:201], v[100:103]
	ds_read_b128 v[172:175], v249 offset:384
	s_waitcnt lgkmcnt(3)
	v_mfma_f32_16x16x32_bf16 v[36:39], v[176:179], v[144:147], v[36:39]
	v_mfma_f32_16x16x32_bf16 v[100:103], v[176:179], v[202:205], v[100:103]
	ds_read_b128 v[176:179], v249 offset:448
	s_waitcnt lgkmcnt(3)
	v_mfma_f32_16x16x32_bf16 v[36:39], v[0:3], v[148:151], v[36:39]
	v_mfma_f32_16x16x32_bf16 v[100:103], v[0:3], v[206:209], v[100:103]
	ds_read_b128 v[0:3], v249 offset:8448
	s_waitcnt lgkmcnt(3)
	v_mfma_f32_16x16x32_bf16 v[36:39], v[168:171], v[152:155], v[36:39]
	v_mfma_f32_16x16x32_bf16 v[100:103], v[168:171], v[224:227], v[100:103]
	ds_read_b128 v[168:171], v249 offset:8512
	s_waitcnt lgkmcnt(3)
	v_mfma_f32_16x16x32_bf16 v[36:39], v[172:175], v[156:159], v[36:39]
	v_mfma_f32_16x16x32_bf16 v[100:103], v[172:175], v[228:231], v[100:103]
	ds_read_b128 v[172:175], v249 offset:8576
	s_waitcnt lgkmcnt(3)
	v_mfma_f32_16x16x32_bf16 v[36:39], v[176:179], v[160:163], v[36:39]
	v_mfma_f32_16x16x32_bf16 v[100:103], v[176:179], v[232:235], v[100:103]
	ds_read_b128 v[176:179], v249 offset:8640
	s_waitcnt lgkmcnt(3)
	v_mfma_f32_16x16x32_bf16 v[40:43], v[0:3], v[132:135], 0
	v_mfma_f32_16x16x32_bf16 v[104:107], v[0:3], v[190:193], 0
	ds_read_b128 v[0:3], v249 offset:8704
	s_waitcnt lgkmcnt(3)
	v_mfma_f32_16x16x32_bf16 v[40:43], v[168:171], v[136:139], v[40:43]
	v_mfma_f32_16x16x32_bf16 v[104:107], v[168:171], v[194:197], v[104:107]
	ds_read_b128 v[168:171], v249 offset:8768
	s_waitcnt lgkmcnt(3)
	v_mfma_f32_16x16x32_bf16 v[40:43], v[172:175], v[140:143], v[40:43]
	v_mfma_f32_16x16x32_bf16 v[104:107], v[172:175], v[198:201], v[104:107]
	ds_read_b128 v[172:175], v249 offset:8832
	s_waitcnt lgkmcnt(3)
	v_mfma_f32_16x16x32_bf16 v[40:43], v[176:179], v[144:147], v[40:43]
	v_mfma_f32_16x16x32_bf16 v[104:107], v[176:179], v[202:205], v[104:107]
	ds_read_b128 v[176:179], v249 offset:8896
	s_waitcnt lgkmcnt(3)
	v_mfma_f32_16x16x32_bf16 v[40:43], v[0:3], v[148:151], v[40:43]
	v_mfma_f32_16x16x32_bf16 v[104:107], v[0:3], v[206:209], v[104:107]
	ds_read_b128 v[0:3], v249 offset:16896
	s_waitcnt lgkmcnt(3)
	v_mfma_f32_16x16x32_bf16 v[40:43], v[168:171], v[152:155], v[40:43]
	v_mfma_f32_16x16x32_bf16 v[104:107], v[168:171], v[224:227], v[104:107]
	ds_read_b128 v[168:171], v249 offset:16960
	s_waitcnt lgkmcnt(3)
	v_mfma_f32_16x16x32_bf16 v[40:43], v[172:175], v[156:159], v[40:43]
	v_mfma_f32_16x16x32_bf16 v[104:107], v[172:175], v[228:231], v[104:107]
	ds_read_b128 v[172:175], v249 offset:17024
	s_waitcnt lgkmcnt(3)
	v_mfma_f32_16x16x32_bf16 v[40:43], v[176:179], v[160:163], v[40:43]
	v_mfma_f32_16x16x32_bf16 v[104:107], v[176:179], v[232:235], v[104:107]
	ds_read_b128 v[176:179], v249 offset:17088
	s_waitcnt lgkmcnt(3)
	v_mfma_f32_16x16x32_bf16 v[44:47], v[0:3], v[132:135], 0
	v_mfma_f32_16x16x32_bf16 v[108:111], v[0:3], v[190:193], 0
	ds_read_b128 v[0:3], v249 offset:17152
	s_waitcnt lgkmcnt(3)
	v_mfma_f32_16x16x32_bf16 v[44:47], v[168:171], v[136:139], v[44:47]
	v_mfma_f32_16x16x32_bf16 v[108:111], v[168:171], v[194:197], v[108:111]
	ds_read_b128 v[168:171], v249 offset:17216
	s_waitcnt lgkmcnt(3)
	v_mfma_f32_16x16x32_bf16 v[44:47], v[172:175], v[140:143], v[44:47]
	v_mfma_f32_16x16x32_bf16 v[108:111], v[172:175], v[198:201], v[108:111]
	ds_read_b128 v[172:175], v249 offset:17280
	s_waitcnt lgkmcnt(3)
	v_mfma_f32_16x16x32_bf16 v[44:47], v[176:179], v[144:147], v[44:47]
	v_mfma_f32_16x16x32_bf16 v[108:111], v[176:179], v[202:205], v[108:111]
	ds_read_b128 v[176:179], v249 offset:17344
	s_waitcnt lgkmcnt(3)
	v_mfma_f32_16x16x32_bf16 v[44:47], v[0:3], v[148:151], v[44:47]
	v_mfma_f32_16x16x32_bf16 v[108:111], v[0:3], v[206:209], v[108:111]
	ds_read_b128 v[0:3], v249 offset:25344
	s_waitcnt lgkmcnt(3)
	v_mfma_f32_16x16x32_bf16 v[44:47], v[168:171], v[152:155], v[44:47]
	v_mfma_f32_16x16x32_bf16 v[108:111], v[168:171], v[224:227], v[108:111]
	ds_read_b128 v[168:171], v249 offset:25408
	s_waitcnt lgkmcnt(3)
	v_mfma_f32_16x16x32_bf16 v[44:47], v[172:175], v[156:159], v[44:47]
	v_mfma_f32_16x16x32_bf16 v[108:111], v[172:175], v[228:231], v[108:111]
	ds_read_b128 v[172:175], v249 offset:25472
	s_waitcnt lgkmcnt(3)
	v_mfma_f32_16x16x32_bf16 v[44:47], v[176:179], v[160:163], v[44:47]
	v_mfma_f32_16x16x32_bf16 v[108:111], v[176:179], v[232:235], v[108:111]
	ds_read_b128 v[176:179], v249 offset:25536
	s_waitcnt lgkmcnt(3)
	v_mfma_f32_16x16x32_bf16 v[48:51], v[0:3], v[132:135], 0
	v_mfma_f32_16x16x32_bf16 v[112:115], v[0:3], v[190:193], 0
	ds_read_b128 v[0:3], v249 offset:25600
	s_waitcnt lgkmcnt(3)
	v_mfma_f32_16x16x32_bf16 v[48:51], v[168:171], v[136:139], v[48:51]
	v_mfma_f32_16x16x32_bf16 v[112:115], v[168:171], v[194:197], v[112:115]
	ds_read_b128 v[168:171], v249 offset:25664
	s_waitcnt lgkmcnt(3)
	v_mfma_f32_16x16x32_bf16 v[48:51], v[172:175], v[140:143], v[48:51]
	v_mfma_f32_16x16x32_bf16 v[112:115], v[172:175], v[198:201], v[112:115]
	ds_read_b128 v[172:175], v249 offset:25728
	s_waitcnt lgkmcnt(3)
	v_mfma_f32_16x16x32_bf16 v[48:51], v[176:179], v[144:147], v[48:51]
	v_mfma_f32_16x16x32_bf16 v[112:115], v[176:179], v[202:205], v[112:115]
	ds_read_b128 v[176:179], v249 offset:25792
	s_waitcnt lgkmcnt(3)
	v_mfma_f32_16x16x32_bf16 v[48:51], v[0:3], v[148:151], v[48:51]
	v_mfma_f32_16x16x32_bf16 v[112:115], v[0:3], v[206:209], v[112:115]
	s_waitcnt lgkmcnt(2)
	v_mfma_f32_16x16x32_bf16 v[48:51], v[168:171], v[152:155], v[48:51]
	v_mfma_f32_16x16x32_bf16 v[112:115], v[168:171], v[224:227], v[112:115]
	s_waitcnt lgkmcnt(1)
	v_mfma_f32_16x16x32_bf16 v[48:51], v[172:175], v[156:159], v[48:51]
	v_mfma_f32_16x16x32_bf16 v[112:115], v[172:175], v[228:231], v[112:115]
	s_waitcnt lgkmcnt(0)
	v_mfma_f32_16x16x32_bf16 v[48:51], v[176:179], v[160:163], v[48:51]
	v_mfma_f32_16x16x32_bf16 v[112:115], v[176:179], v[232:235], v[112:115]
	s_waitcnt vmcnt(0)
	ds_write_b128 v187, v[236:239] offset:33792
	ds_write_b128 v187, v[240:243] offset:33920
	ds_write_b128 v187, v[164:167] offset:34048
	ds_write_b128 v187, v[182:185] offset:34176
	global_load_dwordx4 v[236:239], v[210:211], off offset:2048
	global_load_dwordx4 v[240:243], v[210:211], off offset:2176
	global_load_dwordx4 v[164:167], v[210:211], off offset:2304
	global_load_dwordx4 v[182:185], v[210:211], off offset:2432
	s_waitcnt lgkmcnt(0)
	s_barrier
	ds_read_b128 v[0:3], v249 offset:33792
	ds_read_b128 v[168:171], v249 offset:33856
	ds_read_b128 v[172:175], v249 offset:33920
	ds_read_b128 v[176:179], v249 offset:33984
	s_waitcnt lgkmcnt(3)
	v_mfma_f32_16x16x32_bf16 v[52:55], v[0:3], v[132:135], 0
	v_mfma_f32_16x16x32_bf16 v[116:119], v[0:3], v[190:193], 0
	ds_read_b128 v[0:3], v249 offset:34048
	s_waitcnt lgkmcnt(3)
	v_mfma_f32_16x16x32_bf16 v[52:55], v[168:171], v[136:139], v[52:55]
	v_mfma_f32_16x16x32_bf16 v[116:119], v[168:171], v[194:197], v[116:119]
	ds_read_b128 v[168:171], v249 offset:34112
	s_waitcnt lgkmcnt(3)
	v_mfma_f32_16x16x32_bf16 v[52:55], v[172:175], v[140:143], v[52:55]
	v_mfma_f32_16x16x32_bf16 v[116:119], v[172:175], v[198:201], v[116:119]
	ds_read_b128 v[172:175], v249 offset:34176
	s_waitcnt lgkmcnt(3)
	v_mfma_f32_16x16x32_bf16 v[52:55], v[176:179], v[144:147], v[52:55]
	v_mfma_f32_16x16x32_bf16 v[116:119], v[176:179], v[202:205], v[116:119]
	ds_read_b128 v[176:179], v249 offset:34240
	s_waitcnt lgkmcnt(3)
	v_mfma_f32_16x16x32_bf16 v[52:55], v[0:3], v[148:151], v[52:55]
	v_mfma_f32_16x16x32_bf16 v[116:119], v[0:3], v[206:209], v[116:119]
	ds_read_b128 v[0:3], v249 offset:42240
	s_waitcnt lgkmcnt(3)
	v_mfma_f32_16x16x32_bf16 v[52:55], v[168:171], v[152:155], v[52:55]
	v_mfma_f32_16x16x32_bf16 v[116:119], v[168:171], v[224:227], v[116:119]
	ds_read_b128 v[168:171], v249 offset:42304
	s_waitcnt lgkmcnt(3)
	v_mfma_f32_16x16x32_bf16 v[52:55], v[172:175], v[156:159], v[52:55]
	v_mfma_f32_16x16x32_bf16 v[116:119], v[172:175], v[228:231], v[116:119]
	ds_read_b128 v[172:175], v249 offset:42368
	s_waitcnt lgkmcnt(3)
	v_mfma_f32_16x16x32_bf16 v[52:55], v[176:179], v[160:163], v[52:55]
	v_mfma_f32_16x16x32_bf16 v[116:119], v[176:179], v[232:235], v[116:119]
	ds_read_b128 v[176:179], v249 offset:42432
	s_waitcnt lgkmcnt(3)
	v_mfma_f32_16x16x32_bf16 v[56:59], v[0:3], v[132:135], 0
	v_mfma_f32_16x16x32_bf16 v[120:123], v[0:3], v[190:193], 0
	ds_read_b128 v[0:3], v249 offset:42496
	s_waitcnt lgkmcnt(3)
	v_mfma_f32_16x16x32_bf16 v[56:59], v[168:171], v[136:139], v[56:59]
	v_mfma_f32_16x16x32_bf16 v[120:123], v[168:171], v[194:197], v[120:123]
	ds_read_b128 v[168:171], v249 offset:42560
	s_waitcnt lgkmcnt(3)
	v_mfma_f32_16x16x32_bf16 v[56:59], v[172:175], v[140:143], v[56:59]
	v_mfma_f32_16x16x32_bf16 v[120:123], v[172:175], v[198:201], v[120:123]
	ds_read_b128 v[172:175], v249 offset:42624
	s_waitcnt lgkmcnt(3)
	v_mfma_f32_16x16x32_bf16 v[56:59], v[176:179], v[144:147], v[56:59]
	v_mfma_f32_16x16x32_bf16 v[120:123], v[176:179], v[202:205], v[120:123]
	ds_read_b128 v[176:179], v249 offset:42688
	s_waitcnt lgkmcnt(3)
	v_mfma_f32_16x16x32_bf16 v[56:59], v[0:3], v[148:151], v[56:59]
	v_mfma_f32_16x16x32_bf16 v[120:123], v[0:3], v[206:209], v[120:123]
	ds_read_b128 v[0:3], v249 offset:50688
	s_waitcnt lgkmcnt(3)
	v_mfma_f32_16x16x32_bf16 v[56:59], v[168:171], v[152:155], v[56:59]
	v_mfma_f32_16x16x32_bf16 v[120:123], v[168:171], v[224:227], v[120:123]
	ds_read_b128 v[168:171], v249 offset:50752
	s_waitcnt lgkmcnt(3)
	v_mfma_f32_16x16x32_bf16 v[56:59], v[172:175], v[156:159], v[56:59]
	v_mfma_f32_16x16x32_bf16 v[120:123], v[172:175], v[228:231], v[120:123]
	ds_read_b128 v[172:175], v249 offset:50816
	s_waitcnt lgkmcnt(3)
	v_mfma_f32_16x16x32_bf16 v[56:59], v[176:179], v[160:163], v[56:59]
	v_mfma_f32_16x16x32_bf16 v[120:123], v[176:179], v[232:235], v[120:123]
	ds_read_b128 v[176:179], v249 offset:50880
	s_waitcnt lgkmcnt(3)
	v_mfma_f32_16x16x32_bf16 v[60:63], v[0:3], v[132:135], 0
	v_mfma_f32_16x16x32_bf16 v[124:127], v[0:3], v[190:193], 0
	ds_read_b128 v[0:3], v249 offset:50944
	s_waitcnt lgkmcnt(3)
	v_mfma_f32_16x16x32_bf16 v[60:63], v[168:171], v[136:139], v[60:63]
	v_mfma_f32_16x16x32_bf16 v[124:127], v[168:171], v[194:197], v[124:127]
	ds_read_b128 v[168:171], v249 offset:51008
	s_waitcnt lgkmcnt(3)
	v_mfma_f32_16x16x32_bf16 v[60:63], v[172:175], v[140:143], v[60:63]
	v_mfma_f32_16x16x32_bf16 v[124:127], v[172:175], v[198:201], v[124:127]
	ds_read_b128 v[172:175], v249 offset:51072
	s_waitcnt lgkmcnt(3)
	v_mfma_f32_16x16x32_bf16 v[60:63], v[176:179], v[144:147], v[60:63]
	v_mfma_f32_16x16x32_bf16 v[124:127], v[176:179], v[202:205], v[124:127]
	ds_read_b128 v[176:179], v249 offset:51136
	s_waitcnt lgkmcnt(3)
	v_mfma_f32_16x16x32_bf16 v[60:63], v[0:3], v[148:151], v[60:63]
	v_mfma_f32_16x16x32_bf16 v[124:127], v[0:3], v[206:209], v[124:127]
	ds_read_b128 v[0:3], v249 offset:59136
	s_waitcnt lgkmcnt(3)
	v_mfma_f32_16x16x32_bf16 v[60:63], v[168:171], v[152:155], v[60:63]
	v_mfma_f32_16x16x32_bf16 v[124:127], v[168:171], v[224:227], v[124:127]
	ds_read_b128 v[168:171], v249 offset:59200
	s_waitcnt lgkmcnt(3)
	v_mfma_f32_16x16x32_bf16 v[60:63], v[172:175], v[156:159], v[60:63]
	v_mfma_f32_16x16x32_bf16 v[124:127], v[172:175], v[228:231], v[124:127]
	ds_read_b128 v[172:175], v249 offset:59264
	s_waitcnt lgkmcnt(3)
	v_mfma_f32_16x16x32_bf16 v[60:63], v[176:179], v[160:163], v[60:63]
	v_mfma_f32_16x16x32_bf16 v[124:127], v[176:179], v[232:235], v[124:127]
	ds_read_b128 v[176:179], v249 offset:59328
	s_waitcnt lgkmcnt(3)
	v_mfma_f32_16x16x32_bf16 v[64:67], v[0:3], v[132:135], 0
	v_mfma_f32_16x16x32_bf16 v[128:131], v[0:3], v[190:193], 0
	ds_read_b128 v[0:3], v249 offset:59392
	s_waitcnt lgkmcnt(3)
	v_mfma_f32_16x16x32_bf16 v[64:67], v[168:171], v[136:139], v[64:67]
	v_mfma_f32_16x16x32_bf16 v[128:131], v[168:171], v[194:197], v[128:131]
	ds_read_b128 v[168:171], v249 offset:59456
	s_waitcnt lgkmcnt(3)
	v_mfma_f32_16x16x32_bf16 v[64:67], v[172:175], v[140:143], v[64:67]
	v_mfma_f32_16x16x32_bf16 v[128:131], v[172:175], v[198:201], v[128:131]
	ds_read_b128 v[172:175], v249 offset:59520
	s_waitcnt lgkmcnt(3)
	v_mfma_f32_16x16x32_bf16 v[64:67], v[176:179], v[144:147], v[64:67]
	v_mfma_f32_16x16x32_bf16 v[128:131], v[176:179], v[202:205], v[128:131]
	ds_read_b128 v[176:179], v249 offset:59584
	s_waitcnt lgkmcnt(3)
	v_mfma_f32_16x16x32_bf16 v[64:67], v[0:3], v[148:151], v[64:67]
	v_mfma_f32_16x16x32_bf16 v[128:131], v[0:3], v[206:209], v[128:131]
	s_waitcnt lgkmcnt(2)
	v_mfma_f32_16x16x32_bf16 v[64:67], v[168:171], v[152:155], v[64:67]
	v_mfma_f32_16x16x32_bf16 v[128:131], v[168:171], v[224:227], v[128:131]
	s_waitcnt lgkmcnt(1)
	v_mfma_f32_16x16x32_bf16 v[64:67], v[172:175], v[156:159], v[64:67]
	v_mfma_f32_16x16x32_bf16 v[128:131], v[172:175], v[228:231], v[128:131]
	s_waitcnt lgkmcnt(0)
	v_mfma_f32_16x16x32_bf16 v[64:67], v[176:179], v[160:163], v[64:67]
	v_mfma_f32_16x16x32_bf16 v[128:131], v[176:179], v[232:235], v[128:131]
	s_nop 7
	s_nop 1
	s_mov_b32 s7, 0xf149f2ca
	v_mov_b32_e32 v170, 0x3d800000
	v_mov_b32_e32 v172, 0x3fb8aa3b
	v_max3_f32 v168, v4, v5, v6
	v_max3_f32 v168, v168, v7, v8
	v_max3_f32 v168, v168, v9, v10
	v_max3_f32 v168, v168, v11, v12
	v_max3_f32 v168, v168, v13, v14
	v_max3_f32 v168, v168, v15, v16
	v_max3_f32 v168, v168, v17, v18
	v_max3_f32 v168, v168, v19, v20
	v_max3_f32 v168, v168, v21, v22
	v_max3_f32 v168, v168, v23, v24
	v_max3_f32 v168, v168, v25, v26
	v_max3_f32 v168, v168, v27, v28
	v_max3_f32 v168, v168, v29, v30
	v_max3_f32 v168, v168, v31, v32
	v_max3_f32 v168, v168, v33, v34
	v_max3_f32 v168, v168, v35, v36
	v_max3_f32 v168, v168, v37, v38
	v_max3_f32 v168, v168, v39, v40
	v_max3_f32 v168, v168, v41, v42
	v_max3_f32 v168, v168, v43, v44
	v_max3_f32 v168, v168, v45, v46
	v_max3_f32 v168, v168, v47, v48
	v_max3_f32 v168, v168, v49, v50
	v_max3_f32 v168, v168, v51, v52
	v_max3_f32 v168, v168, v53, v54
	v_max3_f32 v168, v168, v55, v56
	v_max3_f32 v168, v168, v57, v58
	v_max3_f32 v168, v168, v59, v60
	v_max3_f32 v168, v168, v61, v62
	v_max3_f32 v168, v168, v63, v64
	v_max3_f32 v168, v168, v65, v66
	v_max3_f32 v168, v168, s7, v67
	ds_bpermute_b32 v169, v189, v168
	s_waitcnt lgkmcnt(0)
	v_max_f32_e32 v168, v168, v169
	ds_bpermute_b32 v169, v222, v168
	s_waitcnt lgkmcnt(0)
	v_max_f32_e32 v168, v168, v169
	v_mul_f32_e32 v174, 0xbd800000, v168
	v_pk_fma_f32 v[0:1], v[4:5], v[170:171], v[174:175] op_sel_hi:[1,0,0]
	v_pk_fma_f32 v[2:3], v[6:7], v[170:171], v[174:175] op_sel_hi:[1,0,0]
	v_pk_mul_f32 v[0:1], v[0:1], v[172:173] op_sel_hi:[1,0]
	v_pk_mul_f32 v[2:3], v[2:3], v[172:173] op_sel_hi:[1,0]
	v_exp_f32_e32 v4, v0
	v_exp_f32_e32 v5, v1
	v_exp_f32_e32 v6, v2
	v_exp_f32_e32 v7, v3
	v_add_f32_e32 v220, 0, v4
	v_add_f32_e32 v220, v5, v220
	v_add_f32_e32 v220, v6, v220
	v_add_f32_e32 v220, v7, v220
	v_pk_fma_f32 v[0:1], v[8:9], v[170:171], v[174:175] op_sel_hi:[1,0,0]
	v_pk_fma_f32 v[2:3], v[10:11], v[170:171], v[174:175] op_sel_hi:[1,0,0]
	v_pk_mul_f32 v[0:1], v[0:1], v[172:173] op_sel_hi:[1,0]
	v_pk_mul_f32 v[2:3], v[2:3], v[172:173] op_sel_hi:[1,0]
	v_exp_f32_e32 v8, v0
	v_exp_f32_e32 v9, v1
	v_exp_f32_e32 v10, v2
	v_exp_f32_e32 v11, v3
	v_add_f32_e32 v220, v8, v220
	v_add_f32_e32 v220, v9, v220
	v_add_f32_e32 v220, v10, v220
	v_add_f32_e32 v220, v11, v220
	v_cvt_pk_bf16_f32 v132, v4, v5
	v_cvt_pk_bf16_f32 v133, v6, v7
	v_cvt_pk_bf16_f32 v134, v8, v9
	v_cvt_pk_bf16_f32 v135, v10, v11
	v_pk_fma_f32 v[0:1], v[12:13], v[170:171], v[174:175] op_sel_hi:[1,0,0]
	v_pk_fma_f32 v[2:3], v[14:15], v[170:171], v[174:175] op_sel_hi:[1,0,0]
	v_pk_mul_f32 v[0:1], v[0:1], v[172:173] op_sel_hi:[1,0]
	v_pk_mul_f32 v[2:3], v[2:3], v[172:173] op_sel_hi:[1,0]
	v_exp_f32_e32 v12, v0
	v_exp_f32_e32 v13, v1
	v_exp_f32_e32 v14, v2
	v_exp_f32_e32 v15, v3
	v_add_f32_e32 v220, v12, v220
	v_add_f32_e32 v220, v13, v220
	v_add_f32_e32 v220, v14, v220
	v_add_f32_e32 v220, v15, v220
	v_pk_fma_f32 v[0:1], v[16:17], v[170:171], v[174:175] op_sel_hi:[1,0,0]
	v_pk_fma_f32 v[2:3], v[18:19], v[170:171], v[174:175] op_sel_hi:[1,0,0]
	v_pk_mul_f32 v[0:1], v[0:1], v[172:173] op_sel_hi:[1,0]
	v_pk_mul_f32 v[2:3], v[2:3], v[172:173] op_sel_hi:[1,0]
	v_exp_f32_e32 v16, v0
	v_exp_f32_e32 v17, v1
	v_exp_f32_e32 v18, v2
	v_exp_f32_e32 v19, v3
	v_add_f32_e32 v220, v16, v220
	v_add_f32_e32 v220, v17, v220
	v_add_f32_e32 v220, v18, v220
	v_add_f32_e32 v220, v19, v220
	v_cvt_pk_bf16_f32 v136, v12, v13
	v_cvt_pk_bf16_f32 v137, v14, v15
	v_cvt_pk_bf16_f32 v138, v16, v17
	v_cvt_pk_bf16_f32 v139, v18, v19
	v_pk_fma_f32 v[0:1], v[20:21], v[170:171], v[174:175] op_sel_hi:[1,0,0]
	v_pk_fma_f32 v[2:3], v[22:23], v[170:171], v[174:175] op_sel_hi:[1,0,0]
	v_pk_mul_f32 v[0:1], v[0:1], v[172:173] op_sel_hi:[1,0]
	v_pk_mul_f32 v[2:3], v[2:3], v[172:173] op_sel_hi:[1,0]
	v_exp_f32_e32 v20, v0
	v_exp_f32_e32 v21, v1
	v_exp_f32_e32 v22, v2
	v_exp_f32_e32 v23, v3
	v_add_f32_e32 v220, v20, v220
	v_add_f32_e32 v220, v21, v220
	v_add_f32_e32 v220, v22, v220
	v_add_f32_e32 v220, v23, v220
	v_pk_fma_f32 v[0:1], v[24:25], v[170:171], v[174:175] op_sel_hi:[1,0,0]
	v_pk_fma_f32 v[2:3], v[26:27], v[170:171], v[174:175] op_sel_hi:[1,0,0]
	v_pk_mul_f32 v[0:1], v[0:1], v[172:173] op_sel_hi:[1,0]
	v_pk_mul_f32 v[2:3], v[2:3], v[172:173] op_sel_hi:[1,0]
	v_exp_f32_e32 v24, v0
	v_exp_f32_e32 v25, v1
	v_exp_f32_e32 v26, v2
	v_exp_f32_e32 v27, v3
	v_add_f32_e32 v220, v24, v220
	v_add_f32_e32 v220, v25, v220
	v_add_f32_e32 v220, v26, v220
	v_add_f32_e32 v220, v27, v220
	v_cvt_pk_bf16_f32 v140, v20, v21
	v_cvt_pk_bf16_f32 v141, v22, v23
	v_cvt_pk_bf16_f32 v142, v24, v25
	v_cvt_pk_bf16_f32 v143, v26, v27
	v_pk_fma_f32 v[0:1], v[28:29], v[170:171], v[174:175] op_sel_hi:[1,0,0]
	v_pk_fma_f32 v[2:3], v[30:31], v[170:171], v[174:175] op_sel_hi:[1,0,0]
	v_pk_mul_f32 v[0:1], v[0:1], v[172:173] op_sel_hi:[1,0]
	v_pk_mul_f32 v[2:3], v[2:3], v[172:173] op_sel_hi:[1,0]
	v_exp_f32_e32 v28, v0
	v_exp_f32_e32 v29, v1
	v_exp_f32_e32 v30, v2
	v_exp_f32_e32 v31, v3
	v_add_f32_e32 v220, v28, v220
	v_add_f32_e32 v220, v29, v220
	v_add_f32_e32 v220, v30, v220
	v_add_f32_e32 v220, v31, v220
	v_pk_fma_f32 v[0:1], v[32:33], v[170:171], v[174:175] op_sel_hi:[1,0,0]
	v_pk_fma_f32 v[2:3], v[34:35], v[170:171], v[174:175] op_sel_hi:[1,0,0]
	v_pk_mul_f32 v[0:1], v[0:1], v[172:173] op_sel_hi:[1,0]
	v_pk_mul_f32 v[2:3], v[2:3], v[172:173] op_sel_hi:[1,0]
	v_exp_f32_e32 v32, v0
	v_exp_f32_e32 v33, v1
	v_exp_f32_e32 v34, v2
	v_exp_f32_e32 v35, v3
	v_add_f32_e32 v220, v32, v220
	v_add_f32_e32 v220, v33, v220
	v_add_f32_e32 v220, v34, v220
	v_add_f32_e32 v220, v35, v220
	v_cvt_pk_bf16_f32 v144, v28, v29
	v_cvt_pk_bf16_f32 v145, v30, v31
	v_cvt_pk_bf16_f32 v146, v32, v33
	v_cvt_pk_bf16_f32 v147, v34, v35
	v_pk_fma_f32 v[0:1], v[36:37], v[170:171], v[174:175] op_sel_hi:[1,0,0]
	v_pk_fma_f32 v[2:3], v[38:39], v[170:171], v[174:175] op_sel_hi:[1,0,0]
	v_pk_mul_f32 v[0:1], v[0:1], v[172:173] op_sel_hi:[1,0]
	v_pk_mul_f32 v[2:3], v[2:3], v[172:173] op_sel_hi:[1,0]
	v_exp_f32_e32 v36, v0
	v_exp_f32_e32 v37, v1
	v_exp_f32_e32 v38, v2
	v_exp_f32_e32 v39, v3
	v_add_f32_e32 v220, v36, v220
	v_add_f32_e32 v220, v37, v220
	v_add_f32_e32 v220, v38, v220
	v_add_f32_e32 v220, v39, v220
	v_pk_fma_f32 v[0:1], v[40:41], v[170:171], v[174:175] op_sel_hi:[1,0,0]
	v_pk_fma_f32 v[2:3], v[42:43], v[170:171], v[174:175] op_sel_hi:[1,0,0]
	v_pk_mul_f32 v[0:1], v[0:1], v[172:173] op_sel_hi:[1,0]
	v_pk_mul_f32 v[2:3], v[2:3], v[172:173] op_sel_hi:[1,0]
	v_exp_f32_e32 v40, v0
	v_exp_f32_e32 v41, v1
	v_exp_f32_e32 v42, v2
	v_exp_f32_e32 v43, v3
	v_add_f32_e32 v220, v40, v220
	v_add_f32_e32 v220, v41, v220
	v_add_f32_e32 v220, v42, v220
	v_add_f32_e32 v220, v43, v220
	v_cvt_pk_bf16_f32 v148, v36, v37
	v_cvt_pk_bf16_f32 v149, v38, v39
	v_cvt_pk_bf16_f32 v150, v40, v41
	v_cvt_pk_bf16_f32 v151, v42, v43
	v_pk_fma_f32 v[0:1], v[44:45], v[170:171], v[174:175] op_sel_hi:[1,0,0]
	v_pk_fma_f32 v[2:3], v[46:47], v[170:171], v[174:175] op_sel_hi:[1,0,0]
	v_pk_mul_f32 v[0:1], v[0:1], v[172:173] op_sel_hi:[1,0]
	v_pk_mul_f32 v[2:3], v[2:3], v[172:173] op_sel_hi:[1,0]
	v_exp_f32_e32 v44, v0
	v_exp_f32_e32 v45, v1
	v_exp_f32_e32 v46, v2
	v_exp_f32_e32 v47, v3
	v_add_f32_e32 v220, v44, v220
	v_add_f32_e32 v220, v45, v220
	v_add_f32_e32 v220, v46, v220
	v_add_f32_e32 v220, v47, v220
	v_pk_fma_f32 v[0:1], v[48:49], v[170:171], v[174:175] op_sel_hi:[1,0,0]
	v_pk_fma_f32 v[2:3], v[50:51], v[170:171], v[174:175] op_sel_hi:[1,0,0]
	v_pk_mul_f32 v[0:1], v[0:1], v[172:173] op_sel_hi:[1,0]
	v_pk_mul_f32 v[2:3], v[2:3], v[172:173] op_sel_hi:[1,0]
	v_exp_f32_e32 v48, v0
	v_exp_f32_e32 v49, v1
	v_exp_f32_e32 v50, v2
	v_exp_f32_e32 v51, v3
	v_add_f32_e32 v220, v48, v220
	v_add_f32_e32 v220, v49, v220
	v_add_f32_e32 v220, v50, v220
	v_add_f32_e32 v220, v51, v220
	v_cvt_pk_bf16_f32 v152, v44, v45
	v_cvt_pk_bf16_f32 v153, v46, v47
	v_cvt_pk_bf16_f32 v154, v48, v49
	v_cvt_pk_bf16_f32 v155, v50, v51
	v_pk_fma_f32 v[0:1], v[52:53], v[170:171], v[174:175] op_sel_hi:[1,0,0]
	v_pk_fma_f32 v[2:3], v[54:55], v[170:171], v[174:175] op_sel_hi:[1,0,0]
	v_pk_mul_f32 v[0:1], v[0:1], v[172:173] op_sel_hi:[1,0]
	v_pk_mul_f32 v[2:3], v[2:3], v[172:173] op_sel_hi:[1,0]
	v_exp_f32_e32 v52, v0
	v_exp_f32_e32 v53, v1
	v_exp_f32_e32 v54, v2
	v_exp_f32_e32 v55, v3
	v_add_f32_e32 v220, v52, v220
	v_add_f32_e32 v220, v53, v220
	v_add_f32_e32 v220, v54, v220
	v_add_f32_e32 v220, v55, v220
	v_pk_fma_f32 v[0:1], v[56:57], v[170:171], v[174:175] op_sel_hi:[1,0,0]
	v_pk_fma_f32 v[2:3], v[58:59], v[170:171], v[174:175] op_sel_hi:[1,0,0]
	v_pk_mul_f32 v[0:1], v[0:1], v[172:173] op_sel_hi:[1,0]
	v_pk_mul_f32 v[2:3], v[2:3], v[172:173] op_sel_hi:[1,0]
	v_exp_f32_e32 v56, v0
	v_exp_f32_e32 v57, v1
	v_exp_f32_e32 v58, v2
	v_exp_f32_e32 v59, v3
	v_add_f32_e32 v220, v56, v220
	v_add_f32_e32 v220, v57, v220
	v_add_f32_e32 v220, v58, v220
	v_add_f32_e32 v220, v59, v220
	v_cvt_pk_bf16_f32 v156, v52, v53
	v_cvt_pk_bf16_f32 v157, v54, v55
	v_cvt_pk_bf16_f32 v158, v56, v57
	v_cvt_pk_bf16_f32 v159, v58, v59
	v_pk_fma_f32 v[0:1], v[60:61], v[170:171], v[174:175] op_sel_hi:[1,0,0]
	v_pk_fma_f32 v[2:3], v[62:63], v[170:171], v[174:175] op_sel_hi:[1,0,0]
	v_pk_mul_f32 v[0:1], v[0:1], v[172:173] op_sel_hi:[1,0]
	v_pk_mul_f32 v[2:3], v[2:3], v[172:173] op_sel_hi:[1,0]
	v_exp_f32_e32 v60, v0
	v_exp_f32_e32 v61, v1
	v_exp_f32_e32 v62, v2
	v_exp_f32_e32 v63, v3
	v_add_f32_e32 v220, v60, v220
	v_add_f32_e32 v220, v61, v220
	v_add_f32_e32 v220, v62, v220
	v_add_f32_e32 v220, v63, v220
	v_pk_fma_f32 v[0:1], v[64:65], v[170:171], v[174:175] op_sel_hi:[1,0,0]
	v_pk_fma_f32 v[2:3], v[66:67], v[170:171], v[174:175] op_sel_hi:[1,0,0]
	v_pk_mul_f32 v[0:1], v[0:1], v[172:173] op_sel_hi:[1,0]
	v_pk_mul_f32 v[2:3], v[2:3], v[172:173] op_sel_hi:[1,0]
	v_exp_f32_e32 v64, v0
	v_exp_f32_e32 v65, v1
	v_exp_f32_e32 v66, v2
	v_exp_f32_e32 v67, v3
	v_add_f32_e32 v220, v64, v220
	v_add_f32_e32 v220, v65, v220
	v_add_f32_e32 v220, v66, v220
	v_add_f32_e32 v220, v67, v220
	v_cvt_pk_bf16_f32 v160, v60, v61
	v_cvt_pk_bf16_f32 v161, v62, v63
	v_cvt_pk_bf16_f32 v162, v64, v65
	v_cvt_pk_bf16_f32 v163, v66, v67
	ds_bpermute_b32 v169, v189, v220
	s_waitcnt lgkmcnt(0)
	v_add_f32_e32 v220, v220, v169
	ds_bpermute_b32 v169, v222, v220
	s_waitcnt lgkmcnt(0)
	v_add_f32_e32 v220, v220, v169
	v_max3_f32 v168, v68, v69, v70
	v_max3_f32 v168, v168, v71, v72
	v_max3_f32 v168, v168, v73, v74
	v_max3_f32 v168, v168, v75, v76
	v_max3_f32 v168, v168, v77, v78
	v_max3_f32 v168, v168, v79, v80
	v_max3_f32 v168, v168, v81, v82
	v_max3_f32 v168, v168, v83, v84
	v_max3_f32 v168, v168, v85, v86
	v_max3_f32 v168, v168, v87, v88
	v_max3_f32 v168, v168, v89, v90
	v_max3_f32 v168, v168, v91, v92
	v_max3_f32 v168, v168, v93, v94
	v_max3_f32 v168, v168, v95, v96
	v_max3_f32 v168, v168, v97, v98
	v_max3_f32 v168, v168, v99, v100
	v_max3_f32 v168, v168, v101, v102
	v_max3_f32 v168, v168, v103, v104
	v_max3_f32 v168, v168, v105, v106
	v_max3_f32 v168, v168, v107, v108
	v_max3_f32 v168, v168, v109, v110
	v_max3_f32 v168, v168, v111, v112
	v_max3_f32 v168, v168, v113, v114
	v_max3_f32 v168, v168, v115, v116
	v_max3_f32 v168, v168, v117, v118
	v_max3_f32 v168, v168, v119, v120
	v_max3_f32 v168, v168, v121, v122
	v_max3_f32 v168, v168, v123, v124
	v_max3_f32 v168, v168, v125, v126
	v_max3_f32 v168, v168, v127, v128
	v_max3_f32 v168, v168, v129, v130
	v_max3_f32 v168, v168, s7, v131
	ds_bpermute_b32 v169, v189, v168
	s_waitcnt lgkmcnt(0)
	v_max_f32_e32 v168, v168, v169
	ds_bpermute_b32 v169, v222, v168
	s_waitcnt lgkmcnt(0)
	v_max_f32_e32 v168, v168, v169
	v_mul_f32_e32 v174, 0xbd800000, v168
	v_pk_fma_f32 v[0:1], v[68:69], v[170:171], v[174:175] op_sel_hi:[1,0,0]
	v_pk_fma_f32 v[2:3], v[70:71], v[170:171], v[174:175] op_sel_hi:[1,0,0]
	v_pk_mul_f32 v[0:1], v[0:1], v[172:173] op_sel_hi:[1,0]
	v_pk_mul_f32 v[2:3], v[2:3], v[172:173] op_sel_hi:[1,0]
	v_exp_f32_e32 v68, v0
	v_exp_f32_e32 v69, v1
	v_exp_f32_e32 v70, v2
	v_exp_f32_e32 v71, v3
	v_add_f32_e32 v221, 0, v68
	v_add_f32_e32 v221, v69, v221
	v_add_f32_e32 v221, v70, v221
	v_add_f32_e32 v221, v71, v221
	v_pk_fma_f32 v[0:1], v[72:73], v[170:171], v[174:175] op_sel_hi:[1,0,0]
	v_pk_fma_f32 v[2:3], v[74:75], v[170:171], v[174:175] op_sel_hi:[1,0,0]
	v_pk_mul_f32 v[0:1], v[0:1], v[172:173] op_sel_hi:[1,0]
	v_pk_mul_f32 v[2:3], v[2:3], v[172:173] op_sel_hi:[1,0]
	v_exp_f32_e32 v72, v0
	v_exp_f32_e32 v73, v1
	v_exp_f32_e32 v74, v2
	v_exp_f32_e32 v75, v3
	v_add_f32_e32 v221, v72, v221
	v_add_f32_e32 v221, v73, v221
	v_add_f32_e32 v221, v74, v221
	v_add_f32_e32 v221, v75, v221
	v_cvt_pk_bf16_f32 v190, v68, v69
	v_cvt_pk_bf16_f32 v191, v70, v71
	v_cvt_pk_bf16_f32 v192, v72, v73
	v_cvt_pk_bf16_f32 v193, v74, v75
	v_pk_fma_f32 v[0:1], v[76:77], v[170:171], v[174:175] op_sel_hi:[1,0,0]
	v_pk_fma_f32 v[2:3], v[78:79], v[170:171], v[174:175] op_sel_hi:[1,0,0]
	v_pk_mul_f32 v[0:1], v[0:1], v[172:173] op_sel_hi:[1,0]
	v_pk_mul_f32 v[2:3], v[2:3], v[172:173] op_sel_hi:[1,0]
	v_exp_f32_e32 v76, v0
	v_exp_f32_e32 v77, v1
	v_exp_f32_e32 v78, v2
	v_exp_f32_e32 v79, v3
	v_add_f32_e32 v221, v76, v221
	v_add_f32_e32 v221, v77, v221
	v_add_f32_e32 v221, v78, v221
	v_add_f32_e32 v221, v79, v221
	v_pk_fma_f32 v[0:1], v[80:81], v[170:171], v[174:175] op_sel_hi:[1,0,0]
	v_pk_fma_f32 v[2:3], v[82:83], v[170:171], v[174:175] op_sel_hi:[1,0,0]
	v_pk_mul_f32 v[0:1], v[0:1], v[172:173] op_sel_hi:[1,0]
	v_pk_mul_f32 v[2:3], v[2:3], v[172:173] op_sel_hi:[1,0]
	v_exp_f32_e32 v80, v0
	v_exp_f32_e32 v81, v1
	v_exp_f32_e32 v82, v2
	v_exp_f32_e32 v83, v3
	v_add_f32_e32 v221, v80, v221
	v_add_f32_e32 v221, v81, v221
	v_add_f32_e32 v221, v82, v221
	v_add_f32_e32 v221, v83, v221
	v_cvt_pk_bf16_f32 v194, v76, v77
	v_cvt_pk_bf16_f32 v195, v78, v79
	v_cvt_pk_bf16_f32 v196, v80, v81
	v_cvt_pk_bf16_f32 v197, v82, v83
	v_pk_fma_f32 v[0:1], v[84:85], v[170:171], v[174:175] op_sel_hi:[1,0,0]
	v_pk_fma_f32 v[2:3], v[86:87], v[170:171], v[174:175] op_sel_hi:[1,0,0]
	v_pk_mul_f32 v[0:1], v[0:1], v[172:173] op_sel_hi:[1,0]
	v_pk_mul_f32 v[2:3], v[2:3], v[172:173] op_sel_hi:[1,0]
	v_exp_f32_e32 v84, v0
	v_exp_f32_e32 v85, v1
	v_exp_f32_e32 v86, v2
	v_exp_f32_e32 v87, v3
	v_add_f32_e32 v221, v84, v221
	v_add_f32_e32 v221, v85, v221
	v_add_f32_e32 v221, v86, v221
	v_add_f32_e32 v221, v87, v221
	v_pk_fma_f32 v[0:1], v[88:89], v[170:171], v[174:175] op_sel_hi:[1,0,0]
	v_pk_fma_f32 v[2:3], v[90:91], v[170:171], v[174:175] op_sel_hi:[1,0,0]
	v_pk_mul_f32 v[0:1], v[0:1], v[172:173] op_sel_hi:[1,0]
	v_pk_mul_f32 v[2:3], v[2:3], v[172:173] op_sel_hi:[1,0]
	v_exp_f32_e32 v88, v0
	v_exp_f32_e32 v89, v1
	v_exp_f32_e32 v90, v2
	v_exp_f32_e32 v91, v3
	v_add_f32_e32 v221, v88, v221
	v_add_f32_e32 v221, v89, v221
	v_add_f32_e32 v221, v90, v221
	v_add_f32_e32 v221, v91, v221
	v_cvt_pk_bf16_f32 v198, v84, v85
	v_cvt_pk_bf16_f32 v199, v86, v87
	v_cvt_pk_bf16_f32 v200, v88, v89
	v_cvt_pk_bf16_f32 v201, v90, v91
	v_pk_fma_f32 v[0:1], v[92:93], v[170:171], v[174:175] op_sel_hi:[1,0,0]
	v_pk_fma_f32 v[2:3], v[94:95], v[170:171], v[174:175] op_sel_hi:[1,0,0]
	v_pk_mul_f32 v[0:1], v[0:1], v[172:173] op_sel_hi:[1,0]
	v_pk_mul_f32 v[2:3], v[2:3], v[172:173] op_sel_hi:[1,0]
	v_exp_f32_e32 v92, v0
	v_exp_f32_e32 v93, v1
	v_exp_f32_e32 v94, v2
	v_exp_f32_e32 v95, v3
	v_add_f32_e32 v221, v92, v221
	v_add_f32_e32 v221, v93, v221
	v_add_f32_e32 v221, v94, v221
	v_add_f32_e32 v221, v95, v221
	v_pk_fma_f32 v[0:1], v[96:97], v[170:171], v[174:175] op_sel_hi:[1,0,0]
	v_pk_fma_f32 v[2:3], v[98:99], v[170:171], v[174:175] op_sel_hi:[1,0,0]
	v_pk_mul_f32 v[0:1], v[0:1], v[172:173] op_sel_hi:[1,0]
	v_pk_mul_f32 v[2:3], v[2:3], v[172:173] op_sel_hi:[1,0]
	v_exp_f32_e32 v96, v0
	v_exp_f32_e32 v97, v1
	v_exp_f32_e32 v98, v2
	v_exp_f32_e32 v99, v3
	v_add_f32_e32 v221, v96, v221
	v_add_f32_e32 v221, v97, v221
	v_add_f32_e32 v221, v98, v221
	v_add_f32_e32 v221, v99, v221
	v_cvt_pk_bf16_f32 v202, v92, v93
	v_cvt_pk_bf16_f32 v203, v94, v95
	v_cvt_pk_bf16_f32 v204, v96, v97
	v_cvt_pk_bf16_f32 v205, v98, v99
	v_pk_fma_f32 v[0:1], v[100:101], v[170:171], v[174:175] op_sel_hi:[1,0,0]
	v_pk_fma_f32 v[2:3], v[102:103], v[170:171], v[174:175] op_sel_hi:[1,0,0]
	v_pk_mul_f32 v[0:1], v[0:1], v[172:173] op_sel_hi:[1,0]
	v_pk_mul_f32 v[2:3], v[2:3], v[172:173] op_sel_hi:[1,0]
	v_exp_f32_e32 v100, v0
	v_exp_f32_e32 v101, v1
	v_exp_f32_e32 v102, v2
	v_exp_f32_e32 v103, v3
	v_add_f32_e32 v221, v100, v221
	v_add_f32_e32 v221, v101, v221
	v_add_f32_e32 v221, v102, v221
	v_add_f32_e32 v221, v103, v221
	v_pk_fma_f32 v[0:1], v[104:105], v[170:171], v[174:175] op_sel_hi:[1,0,0]
	v_pk_fma_f32 v[2:3], v[106:107], v[170:171], v[174:175] op_sel_hi:[1,0,0]
	v_pk_mul_f32 v[0:1], v[0:1], v[172:173] op_sel_hi:[1,0]
	v_pk_mul_f32 v[2:3], v[2:3], v[172:173] op_sel_hi:[1,0]
	v_exp_f32_e32 v104, v0
	v_exp_f32_e32 v105, v1
	v_exp_f32_e32 v106, v2
	v_exp_f32_e32 v107, v3
	v_add_f32_e32 v221, v104, v221
	v_add_f32_e32 v221, v105, v221
	v_add_f32_e32 v221, v106, v221
	v_add_f32_e32 v221, v107, v221
	v_cvt_pk_bf16_f32 v206, v100, v101
	v_cvt_pk_bf16_f32 v207, v102, v103
	v_cvt_pk_bf16_f32 v208, v104, v105
	v_cvt_pk_bf16_f32 v209, v106, v107
	v_pk_fma_f32 v[0:1], v[108:109], v[170:171], v[174:175] op_sel_hi:[1,0,0]
	v_pk_fma_f32 v[2:3], v[110:111], v[170:171], v[174:175] op_sel_hi:[1,0,0]
	v_pk_mul_f32 v[0:1], v[0:1], v[172:173] op_sel_hi:[1,0]
	v_pk_mul_f32 v[2:3], v[2:3], v[172:173] op_sel_hi:[1,0]
	v_exp_f32_e32 v108, v0
	v_exp_f32_e32 v109, v1
	v_exp_f32_e32 v110, v2
	v_exp_f32_e32 v111, v3
	v_add_f32_e32 v221, v108, v221
	v_add_f32_e32 v221, v109, v221
	v_add_f32_e32 v221, v110, v221
	v_add_f32_e32 v221, v111, v221
	v_pk_fma_f32 v[0:1], v[112:113], v[170:171], v[174:175] op_sel_hi:[1,0,0]
	v_pk_fma_f32 v[2:3], v[114:115], v[170:171], v[174:175] op_sel_hi:[1,0,0]
	v_pk_mul_f32 v[0:1], v[0:1], v[172:173] op_sel_hi:[1,0]
	v_pk_mul_f32 v[2:3], v[2:3], v[172:173] op_sel_hi:[1,0]
	v_exp_f32_e32 v112, v0
	v_exp_f32_e32 v113, v1
	v_exp_f32_e32 v114, v2
	v_exp_f32_e32 v115, v3
	v_add_f32_e32 v221, v112, v221
	v_add_f32_e32 v221, v113, v221
	v_add_f32_e32 v221, v114, v221
	v_add_f32_e32 v221, v115, v221
	v_cvt_pk_bf16_f32 v224, v108, v109
	v_cvt_pk_bf16_f32 v225, v110, v111
	v_cvt_pk_bf16_f32 v226, v112, v113
	v_cvt_pk_bf16_f32 v227, v114, v115
	v_pk_fma_f32 v[0:1], v[116:117], v[170:171], v[174:175] op_sel_hi:[1,0,0]
	v_pk_fma_f32 v[2:3], v[118:119], v[170:171], v[174:175] op_sel_hi:[1,0,0]
	v_pk_mul_f32 v[0:1], v[0:1], v[172:173] op_sel_hi:[1,0]
	v_pk_mul_f32 v[2:3], v[2:3], v[172:173] op_sel_hi:[1,0]
	v_exp_f32_e32 v116, v0
	v_exp_f32_e32 v117, v1
	v_exp_f32_e32 v118, v2
	v_exp_f32_e32 v119, v3
	v_add_f32_e32 v221, v116, v221
	v_add_f32_e32 v221, v117, v221
	v_add_f32_e32 v221, v118, v221
	v_add_f32_e32 v221, v119, v221
	v_pk_fma_f32 v[0:1], v[120:121], v[170:171], v[174:175] op_sel_hi:[1,0,0]
	v_pk_fma_f32 v[2:3], v[122:123], v[170:171], v[174:175] op_sel_hi:[1,0,0]
	v_pk_mul_f32 v[0:1], v[0:1], v[172:173] op_sel_hi:[1,0]
	v_pk_mul_f32 v[2:3], v[2:3], v[172:173] op_sel_hi:[1,0]
	v_exp_f32_e32 v120, v0
	v_exp_f32_e32 v121, v1
	v_exp_f32_e32 v122, v2
	v_exp_f32_e32 v123, v3
	v_add_f32_e32 v221, v120, v221
	v_add_f32_e32 v221, v121, v221
	v_add_f32_e32 v221, v122, v221
	v_add_f32_e32 v221, v123, v221
	v_cvt_pk_bf16_f32 v228, v116, v117
	v_cvt_pk_bf16_f32 v229, v118, v119
	v_cvt_pk_bf16_f32 v230, v120, v121
	v_cvt_pk_bf16_f32 v231, v122, v123
	v_pk_fma_f32 v[0:1], v[124:125], v[170:171], v[174:175] op_sel_hi:[1,0,0]
	v_pk_fma_f32 v[2:3], v[126:127], v[170:171], v[174:175] op_sel_hi:[1,0,0]
	v_pk_mul_f32 v[0:1], v[0:1], v[172:173] op_sel_hi:[1,0]
	v_pk_mul_f32 v[2:3], v[2:3], v[172:173] op_sel_hi:[1,0]
	v_exp_f32_e32 v124, v0
	v_exp_f32_e32 v125, v1
	v_exp_f32_e32 v126, v2
	v_exp_f32_e32 v127, v3
	v_add_f32_e32 v221, v124, v221
	v_add_f32_e32 v221, v125, v221
	v_add_f32_e32 v221, v126, v221
	v_add_f32_e32 v221, v127, v221
	v_pk_fma_f32 v[0:1], v[128:129], v[170:171], v[174:175] op_sel_hi:[1,0,0]
	v_pk_fma_f32 v[2:3], v[130:131], v[170:171], v[174:175] op_sel_hi:[1,0,0]
	v_pk_mul_f32 v[0:1], v[0:1], v[172:173] op_sel_hi:[1,0]
	v_pk_mul_f32 v[2:3], v[2:3], v[172:173] op_sel_hi:[1,0]
	v_exp_f32_e32 v128, v0
	v_exp_f32_e32 v129, v1
	v_exp_f32_e32 v130, v2
	v_exp_f32_e32 v131, v3
	v_add_f32_e32 v221, v128, v221
	v_add_f32_e32 v221, v129, v221
	v_add_f32_e32 v221, v130, v221
	v_add_f32_e32 v221, v131, v221
	v_cvt_pk_bf16_f32 v232, v124, v125
	v_cvt_pk_bf16_f32 v233, v126, v127
	v_cvt_pk_bf16_f32 v234, v128, v129
	v_cvt_pk_bf16_f32 v235, v130, v131
	ds_bpermute_b32 v169, v189, v221
	s_waitcnt lgkmcnt(0)
	v_add_f32_e32 v221, v221, v169
	ds_bpermute_b32 v169, v222, v221
	s_waitcnt lgkmcnt(0)
	v_add_f32_e32 v221, v221, v169
	s_waitcnt vmcnt(0)
	ds_write_b128 v187, v[236:239]
	ds_write_b128 v187, v[240:243] offset:128
	ds_write_b128 v187, v[164:167] offset:256
	ds_write_b128 v187, v[182:185] offset:384
	v_add_co_u32_e32 v218, vcc, 0x80000, v210
	s_nop 1
	v_addc_co_u32_e32 v219, vcc, 0, v211, vcc
	global_load_dwordx4 v[236:239], v[218:219], off offset:2048
	global_load_dwordx4 v[240:243], v[218:219], off offset:2176
	global_load_dwordx4 v[164:167], v[218:219], off offset:2304
	global_load_dwordx4 v[182:185], v[218:219], off offset:2432
	s_waitcnt lgkmcnt(0)
	s_barrier
	ds_read_b64_tr_b16 v[0:1], v180
	ds_read_b64_tr_b16 v[2:3], v180 offset:8448
	ds_read_b64_tr_b16 v[168:169], v180 offset:16896
	ds_read_b64_tr_b16 v[170:171], v180 offset:25344
	ds_read_b64_tr_b16 v[172:173], v180 offset:32
	ds_read_b64_tr_b16 v[174:175], v180 offset:8480
	ds_read_b64_tr_b16 v[176:177], v180 offset:16928
	ds_read_b64_tr_b16 v[178:179], v180 offset:25376
	s_waitcnt lgkmcnt(4)
	v_mfma_f32_16x16x32_bf16 v[4:7], v[0:3], v[132:135], 0
	v_mfma_f32_16x16x32_bf16 v[68:71], v[0:3], v[190:193], 0
	v_mfma_f32_16x16x32_bf16 v[4:7], v[168:171], v[136:139], v[4:7]
	v_mfma_f32_16x16x32_bf16 v[68:71], v[168:171], v[194:197], v[68:71]
	ds_read_b64_tr_b16 v[0:1], v180 offset:64
	ds_read_b64_tr_b16 v[2:3], v180 offset:8512
	ds_read_b64_tr_b16 v[168:169], v180 offset:16960
	ds_read_b64_tr_b16 v[170:171], v180 offset:25408
	s_waitcnt lgkmcnt(4)
	v_mfma_f32_16x16x32_bf16 v[8:11], v[172:175], v[132:135], 0
	v_mfma_f32_16x16x32_bf16 v[72:75], v[172:175], v[190:193], 0
	v_mfma_f32_16x16x32_bf16 v[8:11], v[176:179], v[136:139], v[8:11]
	v_mfma_f32_16x16x32_bf16 v[72:75], v[176:179], v[194:197], v[72:75]
	ds_read_b64_tr_b16 v[172:173], v180 offset:96
	ds_read_b64_tr_b16 v[174:175], v180 offset:8544
	ds_read_b64_tr_b16 v[176:177], v180 offset:16992
	ds_read_b64_tr_b16 v[178:179], v180 offset:25440
	s_waitcnt lgkmcnt(4)
	v_mfma_f32_16x16x32_bf16 v[12:15], v[0:3], v[132:135], 0
	v_mfma_f32_16x16x32_bf16 v[76:79], v[0:3], v[190:193], 0
	v_mfma_f32_16x16x32_bf16 v[12:15], v[168:171], v[136:139], v[12:15]
	v_mfma_f32_16x16x32_bf16 v[76:79], v[168:171], v[194:197], v[76:79]
	ds_read_b64_tr_b16 v[0:1], v180 offset:128
	ds_read_b64_tr_b16 v[2:3], v180 offset:8576
	ds_read_b64_tr_b16 v[168:169], v180 offset:17024
	ds_read_b64_tr_b16 v[170:171], v180 offset:25472
	s_waitcnt lgkmcnt(4)
	v_mfma_f32_16x16x32_bf16 v[16:19], v[172:175], v[132:135], 0
	v_mfma_f32_16x16x32_bf16 v[80:83], v[172:175], v[190:193], 0
	v_mfma_f32_16x16x32_bf16 v[16:19], v[176:179], v[136:139], v[16:19]
	v_mfma_f32_16x16x32_bf16 v[80:83], v[176:179], v[194:197], v[80:83]
	ds_read_b64_tr_b16 v[172:173], v180 offset:160
	ds_read_b64_tr_b16 v[174:175], v180 offset:8608
	ds_read_b64_tr_b16 v[176:177], v180 offset:17056
	ds_read_b64_tr_b16 v[178:179], v180 offset:25504
	s_waitcnt lgkmcnt(4)
	v_mfma_f32_16x16x32_bf16 v[20:23], v[0:3], v[132:135], 0
	v_mfma_f32_16x16x32_bf16 v[84:87], v[0:3], v[190:193], 0
	v_mfma_f32_16x16x32_bf16 v[20:23], v[168:171], v[136:139], v[20:23]
	v_mfma_f32_16x16x32_bf16 v[84:87], v[168:171], v[194:197], v[84:87]
	ds_read_b64_tr_b16 v[0:1], v180 offset:192
	ds_read_b64_tr_b16 v[2:3], v180 offset:8640
	ds_read_b64_tr_b16 v[168:169], v180 offset:17088
	ds_read_b64_tr_b16 v[170:171], v180 offset:25536
	s_waitcnt lgkmcnt(4)
	v_mfma_f32_16x16x32_bf16 v[24:27], v[172:175], v[132:135], 0
	v_mfma_f32_16x16x32_bf16 v[88:91], v[172:175], v[190:193], 0
	v_mfma_f32_16x16x32_bf16 v[24:27], v[176:179], v[136:139], v[24:27]
	v_mfma_f32_16x16x32_bf16 v[88:91], v[176:179], v[194:197], v[88:91]
	ds_read_b64_tr_b16 v[172:173], v180 offset:224
	ds_read_b64_tr_b16 v[174:175], v180 offset:8672
	ds_read_b64_tr_b16 v[176:177], v180 offset:17120
	ds_read_b64_tr_b16 v[178:179], v180 offset:25568
	s_waitcnt lgkmcnt(4)
	v_mfma_f32_16x16x32_bf16 v[28:31], v[0:3], v[132:135], 0
	v_mfma_f32_16x16x32_bf16 v[92:95], v[0:3], v[190:193], 0
	v_mfma_f32_16x16x32_bf16 v[28:31], v[168:171], v[136:139], v[28:31]
	v_mfma_f32_16x16x32_bf16 v[92:95], v[168:171], v[194:197], v[92:95]
	ds_read_b64_tr_b16 v[0:1], v180 offset:256
	ds_read_b64_tr_b16 v[2:3], v180 offset:8704
	ds_read_b64_tr_b16 v[168:169], v180 offset:17152
	ds_read_b64_tr_b16 v[170:171], v180 offset:25600
	s_waitcnt lgkmcnt(4)
	v_mfma_f32_16x16x32_bf16 v[32:35], v[172:175], v[132:135], 0
	v_mfma_f32_16x16x32_bf16 v[96:99], v[172:175], v[190:193], 0
	v_mfma_f32_16x16x32_bf16 v[32:35], v[176:179], v[136:139], v[32:35]
	v_mfma_f32_16x16x32_bf16 v[96:99], v[176:179], v[194:197], v[96:99]
	ds_read_b64_tr_b16 v[172:173], v180 offset:288
	ds_read_b64_tr_b16 v[174:175], v180 offset:8736
	ds_read_b64_tr_b16 v[176:177], v180 offset:17184
	ds_read_b64_tr_b16 v[178:179], v180 offset:25632
	s_waitcnt lgkmcnt(4)
	v_mfma_f32_16x16x32_bf16 v[36:39], v[0:3], v[132:135], 0
	v_mfma_f32_16x16x32_bf16 v[100:103], v[0:3], v[190:193], 0
	v_mfma_f32_16x16x32_bf16 v[36:39], v[168:171], v[136:139], v[36:39]
	v_mfma_f32_16x16x32_bf16 v[100:103], v[168:171], v[194:197], v[100:103]
	ds_read_b64_tr_b16 v[0:1], v180 offset:320
	ds_read_b64_tr_b16 v[2:3], v180 offset:8768
	ds_read_b64_tr_b16 v[168:169], v180 offset:17216
	ds_read_b64_tr_b16 v[170:171], v180 offset:25664
	s_waitcnt lgkmcnt(4)
	v_mfma_f32_16x16x32_bf16 v[40:43], v[172:175], v[132:135], 0
	v_mfma_f32_16x16x32_bf16 v[104:107], v[172:175], v[190:193], 0
	v_mfma_f32_16x16x32_bf16 v[40:43], v[176:179], v[136:139], v[40:43]
	v_mfma_f32_16x16x32_bf16 v[104:107], v[176:179], v[194:197], v[104:107]
	ds_read_b64_tr_b16 v[172:173], v180 offset:352
	ds_read_b64_tr_b16 v[174:175], v180 offset:8800
	ds_read_b64_tr_b16 v[176:177], v180 offset:17248
	ds_read_b64_tr_b16 v[178:179], v180 offset:25696
	s_waitcnt lgkmcnt(4)
	v_mfma_f32_16x16x32_bf16 v[44:47], v[0:3], v[132:135], 0
	v_mfma_f32_16x16x32_bf16 v[108:111], v[0:3], v[190:193], 0
	v_mfma_f32_16x16x32_bf16 v[44:47], v[168:171], v[136:139], v[44:47]
	v_mfma_f32_16x16x32_bf16 v[108:111], v[168:171], v[194:197], v[108:111]
	ds_read_b64_tr_b16 v[0:1], v180 offset:384
	ds_read_b64_tr_b16 v[2:3], v180 offset:8832
	ds_read_b64_tr_b16 v[168:169], v180 offset:17280
	ds_read_b64_tr_b16 v[170:171], v180 offset:25728
	s_waitcnt lgkmcnt(4)
	v_mfma_f32_16x16x32_bf16 v[48:51], v[172:175], v[132:135], 0
	v_mfma_f32_16x16x32_bf16 v[112:115], v[172:175], v[190:193], 0
	v_mfma_f32_16x16x32_bf16 v[48:51], v[176:179], v[136:139], v[48:51]
	v_mfma_f32_16x16x32_bf16 v[112:115], v[176:179], v[194:197], v[112:115]
	ds_read_b64_tr_b16 v[172:173], v180 offset:416
	ds_read_b64_tr_b16 v[174:175], v180 offset:8864
	ds_read_b64_tr_b16 v[176:177], v180 offset:17312
	ds_read_b64_tr_b16 v[178:179], v180 offset:25760
	s_waitcnt lgkmcnt(4)
	v_mfma_f32_16x16x32_bf16 v[52:55], v[0:3], v[132:135], 0
	v_mfma_f32_16x16x32_bf16 v[116:119], v[0:3], v[190:193], 0
	v_mfma_f32_16x16x32_bf16 v[52:55], v[168:171], v[136:139], v[52:55]
	v_mfma_f32_16x16x32_bf16 v[116:119], v[168:171], v[194:197], v[116:119]
	ds_read_b64_tr_b16 v[0:1], v180 offset:448
	ds_read_b64_tr_b16 v[2:3], v180 offset:8896
	ds_read_b64_tr_b16 v[168:169], v180 offset:17344
	ds_read_b64_tr_b16 v[170:171], v180 offset:25792
	s_waitcnt lgkmcnt(4)
	v_mfma_f32_16x16x32_bf16 v[56:59], v[172:175], v[132:135], 0
	v_mfma_f32_16x16x32_bf16 v[120:123], v[172:175], v[190:193], 0
	v_mfma_f32_16x16x32_bf16 v[56:59], v[176:179], v[136:139], v[56:59]
	v_mfma_f32_16x16x32_bf16 v[120:123], v[176:179], v[194:197], v[120:123]
	ds_read_b64_tr_b16 v[172:173], v180 offset:480
	ds_read_b64_tr_b16 v[174:175], v180 offset:8928
	ds_read_b64_tr_b16 v[176:177], v180 offset:17376
	ds_read_b64_tr_b16 v[178:179], v180 offset:25824
	s_waitcnt lgkmcnt(4)
	v_mfma_f32_16x16x32_bf16 v[60:63], v[0:3], v[132:135], 0
	v_mfma_f32_16x16x32_bf16 v[124:127], v[0:3], v[190:193], 0
	v_mfma_f32_16x16x32_bf16 v[60:63], v[168:171], v[136:139], v[60:63]
	v_mfma_f32_16x16x32_bf16 v[124:127], v[168:171], v[194:197], v[124:127]
	s_waitcnt lgkmcnt(0)
	v_mfma_f32_16x16x32_bf16 v[64:67], v[172:175], v[132:135], 0
	v_mfma_f32_16x16x32_bf16 v[128:131], v[172:175], v[190:193], 0
	v_mfma_f32_16x16x32_bf16 v[64:67], v[176:179], v[136:139], v[64:67]
	v_mfma_f32_16x16x32_bf16 v[128:131], v[176:179], v[194:197], v[128:131]
	s_waitcnt vmcnt(0)
	ds_write_b128 v187, v[236:239] offset:33792
	ds_write_b128 v187, v[240:243] offset:33920
	ds_write_b128 v187, v[164:167] offset:34048
	ds_write_b128 v187, v[182:185] offset:34176
	v_add_co_u32_e32 v218, vcc, 0x100000, v210
	s_nop 1
	v_addc_co_u32_e32 v219, vcc, 0, v211, vcc
	global_load_dwordx4 v[236:239], v[218:219], off offset:2048
	global_load_dwordx4 v[240:243], v[218:219], off offset:2176
	global_load_dwordx4 v[164:167], v[218:219], off offset:2304
	global_load_dwordx4 v[182:185], v[218:219], off offset:2432
	s_waitcnt lgkmcnt(0)
	s_barrier
	ds_read_b64_tr_b16 v[0:1], v180 offset:33792
	ds_read_b64_tr_b16 v[2:3], v180 offset:42240
	ds_read_b64_tr_b16 v[168:169], v180 offset:50688
	ds_read_b64_tr_b16 v[170:171], v180 offset:59136
	ds_read_b64_tr_b16 v[172:173], v180 offset:33824
	ds_read_b64_tr_b16 v[174:175], v180 offset:42272
	ds_read_b64_tr_b16 v[176:177], v180 offset:50720
	ds_read_b64_tr_b16 v[178:179], v180 offset:59168
	s_waitcnt lgkmcnt(4)
	v_mfma_f32_16x16x32_bf16 v[4:7], v[0:3], v[140:143], v[4:7]
	v_mfma_f32_16x16x32_bf16 v[68:71], v[0:3], v[198:201], v[68:71]
	v_mfma_f32_16x16x32_bf16 v[4:7], v[168:171], v[144:147], v[4:7]
	v_mfma_f32_16x16x32_bf16 v[68:71], v[168:171], v[202:205], v[68:71]
	ds_read_b64_tr_b16 v[0:1], v180 offset:33856
	ds_read_b64_tr_b16 v[2:3], v180 offset:42304
	ds_read_b64_tr_b16 v[168:169], v180 offset:50752
	ds_read_b64_tr_b16 v[170:171], v180 offset:59200
	s_waitcnt lgkmcnt(4)
	v_mfma_f32_16x16x32_bf16 v[8:11], v[172:175], v[140:143], v[8:11]
	v_mfma_f32_16x16x32_bf16 v[72:75], v[172:175], v[198:201], v[72:75]
	v_mfma_f32_16x16x32_bf16 v[8:11], v[176:179], v[144:147], v[8:11]
	v_mfma_f32_16x16x32_bf16 v[72:75], v[176:179], v[202:205], v[72:75]
	ds_read_b64_tr_b16 v[172:173], v180 offset:33888
	ds_read_b64_tr_b16 v[174:175], v180 offset:42336
	ds_read_b64_tr_b16 v[176:177], v180 offset:50784
	ds_read_b64_tr_b16 v[178:179], v180 offset:59232
	s_waitcnt lgkmcnt(4)
	v_mfma_f32_16x16x32_bf16 v[12:15], v[0:3], v[140:143], v[12:15]
	v_mfma_f32_16x16x32_bf16 v[76:79], v[0:3], v[198:201], v[76:79]
	v_mfma_f32_16x16x32_bf16 v[12:15], v[168:171], v[144:147], v[12:15]
	v_mfma_f32_16x16x32_bf16 v[76:79], v[168:171], v[202:205], v[76:79]
	ds_read_b64_tr_b16 v[0:1], v180 offset:33920
	ds_read_b64_tr_b16 v[2:3], v180 offset:42368
	ds_read_b64_tr_b16 v[168:169], v180 offset:50816
	ds_read_b64_tr_b16 v[170:171], v180 offset:59264
	s_waitcnt lgkmcnt(4)
	v_mfma_f32_16x16x32_bf16 v[16:19], v[172:175], v[140:143], v[16:19]
	v_mfma_f32_16x16x32_bf16 v[80:83], v[172:175], v[198:201], v[80:83]
	v_mfma_f32_16x16x32_bf16 v[16:19], v[176:179], v[144:147], v[16:19]
	v_mfma_f32_16x16x32_bf16 v[80:83], v[176:179], v[202:205], v[80:83]
	ds_read_b64_tr_b16 v[172:173], v180 offset:33952
	ds_read_b64_tr_b16 v[174:175], v180 offset:42400
	ds_read_b64_tr_b16 v[176:177], v180 offset:50848
	ds_read_b64_tr_b16 v[178:179], v180 offset:59296
	s_waitcnt lgkmcnt(4)
	v_mfma_f32_16x16x32_bf16 v[20:23], v[0:3], v[140:143], v[20:23]
	v_mfma_f32_16x16x32_bf16 v[84:87], v[0:3], v[198:201], v[84:87]
	v_mfma_f32_16x16x32_bf16 v[20:23], v[168:171], v[144:147], v[20:23]
	v_mfma_f32_16x16x32_bf16 v[84:87], v[168:171], v[202:205], v[84:87]
	ds_read_b64_tr_b16 v[0:1], v180 offset:33984
	ds_read_b64_tr_b16 v[2:3], v180 offset:42432
	ds_read_b64_tr_b16 v[168:169], v180 offset:50880
	ds_read_b64_tr_b16 v[170:171], v180 offset:59328
	s_waitcnt lgkmcnt(4)
	v_mfma_f32_16x16x32_bf16 v[24:27], v[172:175], v[140:143], v[24:27]
	v_mfma_f32_16x16x32_bf16 v[88:91], v[172:175], v[198:201], v[88:91]
	v_mfma_f32_16x16x32_bf16 v[24:27], v[176:179], v[144:147], v[24:27]
	v_mfma_f32_16x16x32_bf16 v[88:91], v[176:179], v[202:205], v[88:91]
	ds_read_b64_tr_b16 v[172:173], v180 offset:34016
	ds_read_b64_tr_b16 v[174:175], v180 offset:42464
	ds_read_b64_tr_b16 v[176:177], v180 offset:50912
	ds_read_b64_tr_b16 v[178:179], v180 offset:59360
	s_waitcnt lgkmcnt(4)
	v_mfma_f32_16x16x32_bf16 v[28:31], v[0:3], v[140:143], v[28:31]
	v_mfma_f32_16x16x32_bf16 v[92:95], v[0:3], v[198:201], v[92:95]
	v_mfma_f32_16x16x32_bf16 v[28:31], v[168:171], v[144:147], v[28:31]
	v_mfma_f32_16x16x32_bf16 v[92:95], v[168:171], v[202:205], v[92:95]
	ds_read_b64_tr_b16 v[0:1], v180 offset:34048
	ds_read_b64_tr_b16 v[2:3], v180 offset:42496
	ds_read_b64_tr_b16 v[168:169], v180 offset:50944
	ds_read_b64_tr_b16 v[170:171], v180 offset:59392
	s_waitcnt lgkmcnt(4)
	v_mfma_f32_16x16x32_bf16 v[32:35], v[172:175], v[140:143], v[32:35]
	v_mfma_f32_16x16x32_bf16 v[96:99], v[172:175], v[198:201], v[96:99]
	v_mfma_f32_16x16x32_bf16 v[32:35], v[176:179], v[144:147], v[32:35]
	v_mfma_f32_16x16x32_bf16 v[96:99], v[176:179], v[202:205], v[96:99]
	ds_read_b64_tr_b16 v[172:173], v180 offset:34080
	ds_read_b64_tr_b16 v[174:175], v180 offset:42528
	ds_read_b64_tr_b16 v[176:177], v180 offset:50976
	ds_read_b64_tr_b16 v[178:179], v180 offset:59424
	s_waitcnt lgkmcnt(4)
	v_mfma_f32_16x16x32_bf16 v[36:39], v[0:3], v[140:143], v[36:39]
	v_mfma_f32_16x16x32_bf16 v[100:103], v[0:3], v[198:201], v[100:103]
	v_mfma_f32_16x16x32_bf16 v[36:39], v[168:171], v[144:147], v[36:39]
	v_mfma_f32_16x16x32_bf16 v[100:103], v[168:171], v[202:205], v[100:103]
	ds_read_b64_tr_b16 v[0:1], v180 offset:34112
	ds_read_b64_tr_b16 v[2:3], v180 offset:42560
	ds_read_b64_tr_b16 v[168:169], v180 offset:51008
	ds_read_b64_tr_b16 v[170:171], v180 offset:59456
	s_waitcnt lgkmcnt(4)
	v_mfma_f32_16x16x32_bf16 v[40:43], v[172:175], v[140:143], v[40:43]
	v_mfma_f32_16x16x32_bf16 v[104:107], v[172:175], v[198:201], v[104:107]
	v_mfma_f32_16x16x32_bf16 v[40:43], v[176:179], v[144:147], v[40:43]
	v_mfma_f32_16x16x32_bf16 v[104:107], v[176:179], v[202:205], v[104:107]
	ds_read_b64_tr_b16 v[172:173], v180 offset:34144
	ds_read_b64_tr_b16 v[174:175], v180 offset:42592
	ds_read_b64_tr_b16 v[176:177], v180 offset:51040
	ds_read_b64_tr_b16 v[178:179], v180 offset:59488
	s_waitcnt lgkmcnt(4)
	v_mfma_f32_16x16x32_bf16 v[44:47], v[0:3], v[140:143], v[44:47]
	v_mfma_f32_16x16x32_bf16 v[108:111], v[0:3], v[198:201], v[108:111]
	v_mfma_f32_16x16x32_bf16 v[44:47], v[168:171], v[144:147], v[44:47]
	v_mfma_f32_16x16x32_bf16 v[108:111], v[168:171], v[202:205], v[108:111]
	ds_read_b64_tr_b16 v[0:1], v180 offset:34176
	ds_read_b64_tr_b16 v[2:3], v180 offset:42624
	ds_read_b64_tr_b16 v[168:169], v180 offset:51072
	ds_read_b64_tr_b16 v[170:171], v180 offset:59520
	s_waitcnt lgkmcnt(4)
	v_mfma_f32_16x16x32_bf16 v[48:51], v[172:175], v[140:143], v[48:51]
	v_mfma_f32_16x16x32_bf16 v[112:115], v[172:175], v[198:201], v[112:115]
	v_mfma_f32_16x16x32_bf16 v[48:51], v[176:179], v[144:147], v[48:51]
	v_mfma_f32_16x16x32_bf16 v[112:115], v[176:179], v[202:205], v[112:115]
	ds_read_b64_tr_b16 v[172:173], v180 offset:34208
	ds_read_b64_tr_b16 v[174:175], v180 offset:42656
	ds_read_b64_tr_b16 v[176:177], v180 offset:51104
	ds_read_b64_tr_b16 v[178:179], v180 offset:59552
	s_waitcnt lgkmcnt(4)
	v_mfma_f32_16x16x32_bf16 v[52:55], v[0:3], v[140:143], v[52:55]
	v_mfma_f32_16x16x32_bf16 v[116:119], v[0:3], v[198:201], v[116:119]
	v_mfma_f32_16x16x32_bf16 v[52:55], v[168:171], v[144:147], v[52:55]
	v_mfma_f32_16x16x32_bf16 v[116:119], v[168:171], v[202:205], v[116:119]
	ds_read_b64_tr_b16 v[0:1], v180 offset:34240
	ds_read_b64_tr_b16 v[2:3], v180 offset:42688
	ds_read_b64_tr_b16 v[168:169], v180 offset:51136
	ds_read_b64_tr_b16 v[170:171], v180 offset:59584
	s_waitcnt lgkmcnt(4)
	v_mfma_f32_16x16x32_bf16 v[56:59], v[172:175], v[140:143], v[56:59]
	v_mfma_f32_16x16x32_bf16 v[120:123], v[172:175], v[198:201], v[120:123]
	v_mfma_f32_16x16x32_bf16 v[56:59], v[176:179], v[144:147], v[56:59]
	v_mfma_f32_16x16x32_bf16 v[120:123], v[176:179], v[202:205], v[120:123]
	ds_read_b64_tr_b16 v[172:173], v180 offset:34272
	ds_read_b64_tr_b16 v[174:175], v180 offset:42720
	ds_read_b64_tr_b16 v[176:177], v180 offset:51168
	ds_read_b64_tr_b16 v[178:179], v180 offset:59616
	s_waitcnt lgkmcnt(4)
	v_mfma_f32_16x16x32_bf16 v[60:63], v[0:3], v[140:143], v[60:63]
	v_mfma_f32_16x16x32_bf16 v[124:127], v[0:3], v[198:201], v[124:127]
	v_mfma_f32_16x16x32_bf16 v[60:63], v[168:171], v[144:147], v[60:63]
	v_mfma_f32_16x16x32_bf16 v[124:127], v[168:171], v[202:205], v[124:127]
	s_waitcnt lgkmcnt(0)
	v_mfma_f32_16x16x32_bf16 v[64:67], v[172:175], v[140:143], v[64:67]
	v_mfma_f32_16x16x32_bf16 v[128:131], v[172:175], v[198:201], v[128:131]
	v_mfma_f32_16x16x32_bf16 v[64:67], v[176:179], v[144:147], v[64:67]
	v_mfma_f32_16x16x32_bf16 v[128:131], v[176:179], v[202:205], v[128:131]
	s_waitcnt vmcnt(0)
	ds_write_b128 v187, v[236:239]
	ds_write_b128 v187, v[240:243] offset:128
	ds_write_b128 v187, v[164:167] offset:256
	ds_write_b128 v187, v[182:185] offset:384
	v_add_co_u32_e32 v218, vcc, 0x180000, v210
	s_nop 1
	v_addc_co_u32_e32 v219, vcc, 0, v211, vcc
	global_load_dwordx4 v[236:239], v[218:219], off offset:2048
	global_load_dwordx4 v[240:243], v[218:219], off offset:2176
	global_load_dwordx4 v[164:167], v[218:219], off offset:2304
	global_load_dwordx4 v[182:185], v[218:219], off offset:2432
	s_waitcnt lgkmcnt(0)
	s_barrier
	ds_read_b64_tr_b16 v[0:1], v180
	ds_read_b64_tr_b16 v[2:3], v180 offset:8448
	ds_read_b64_tr_b16 v[168:169], v180 offset:16896
	ds_read_b64_tr_b16 v[170:171], v180 offset:25344
	ds_read_b64_tr_b16 v[172:173], v180 offset:32
	ds_read_b64_tr_b16 v[174:175], v180 offset:8480
	ds_read_b64_tr_b16 v[176:177], v180 offset:16928
	ds_read_b64_tr_b16 v[178:179], v180 offset:25376
	s_waitcnt lgkmcnt(4)
	v_mfma_f32_16x16x32_bf16 v[4:7], v[0:3], v[148:151], v[4:7]
	v_mfma_f32_16x16x32_bf16 v[68:71], v[0:3], v[206:209], v[68:71]
	v_mfma_f32_16x16x32_bf16 v[4:7], v[168:171], v[152:155], v[4:7]
	v_mfma_f32_16x16x32_bf16 v[68:71], v[168:171], v[224:227], v[68:71]
	ds_read_b64_tr_b16 v[0:1], v180 offset:64
	ds_read_b64_tr_b16 v[2:3], v180 offset:8512
	ds_read_b64_tr_b16 v[168:169], v180 offset:16960
	ds_read_b64_tr_b16 v[170:171], v180 offset:25408
	s_waitcnt lgkmcnt(4)
	v_mfma_f32_16x16x32_bf16 v[8:11], v[172:175], v[148:151], v[8:11]
	v_mfma_f32_16x16x32_bf16 v[72:75], v[172:175], v[206:209], v[72:75]
	v_mfma_f32_16x16x32_bf16 v[8:11], v[176:179], v[152:155], v[8:11]
	v_mfma_f32_16x16x32_bf16 v[72:75], v[176:179], v[224:227], v[72:75]
	ds_read_b64_tr_b16 v[172:173], v180 offset:96
	ds_read_b64_tr_b16 v[174:175], v180 offset:8544
	ds_read_b64_tr_b16 v[176:177], v180 offset:16992
	ds_read_b64_tr_b16 v[178:179], v180 offset:25440
	s_waitcnt lgkmcnt(4)
	v_mfma_f32_16x16x32_bf16 v[12:15], v[0:3], v[148:151], v[12:15]
	v_mfma_f32_16x16x32_bf16 v[76:79], v[0:3], v[206:209], v[76:79]
	v_mfma_f32_16x16x32_bf16 v[12:15], v[168:171], v[152:155], v[12:15]
	v_mfma_f32_16x16x32_bf16 v[76:79], v[168:171], v[224:227], v[76:79]
	ds_read_b64_tr_b16 v[0:1], v180 offset:128
	ds_read_b64_tr_b16 v[2:3], v180 offset:8576
	ds_read_b64_tr_b16 v[168:169], v180 offset:17024
	ds_read_b64_tr_b16 v[170:171], v180 offset:25472
	s_waitcnt lgkmcnt(4)
	v_mfma_f32_16x16x32_bf16 v[16:19], v[172:175], v[148:151], v[16:19]
	v_mfma_f32_16x16x32_bf16 v[80:83], v[172:175], v[206:209], v[80:83]
	v_mfma_f32_16x16x32_bf16 v[16:19], v[176:179], v[152:155], v[16:19]
	v_mfma_f32_16x16x32_bf16 v[80:83], v[176:179], v[224:227], v[80:83]
	ds_read_b64_tr_b16 v[172:173], v180 offset:160
	ds_read_b64_tr_b16 v[174:175], v180 offset:8608
	ds_read_b64_tr_b16 v[176:177], v180 offset:17056
	ds_read_b64_tr_b16 v[178:179], v180 offset:25504
	s_waitcnt lgkmcnt(4)
	v_mfma_f32_16x16x32_bf16 v[20:23], v[0:3], v[148:151], v[20:23]
	v_mfma_f32_16x16x32_bf16 v[84:87], v[0:3], v[206:209], v[84:87]
	v_mfma_f32_16x16x32_bf16 v[20:23], v[168:171], v[152:155], v[20:23]
	v_mfma_f32_16x16x32_bf16 v[84:87], v[168:171], v[224:227], v[84:87]
	ds_read_b64_tr_b16 v[0:1], v180 offset:192
	ds_read_b64_tr_b16 v[2:3], v180 offset:8640
	ds_read_b64_tr_b16 v[168:169], v180 offset:17088
	ds_read_b64_tr_b16 v[170:171], v180 offset:25536
	s_waitcnt lgkmcnt(4)
	v_mfma_f32_16x16x32_bf16 v[24:27], v[172:175], v[148:151], v[24:27]
	v_mfma_f32_16x16x32_bf16 v[88:91], v[172:175], v[206:209], v[88:91]
	v_mfma_f32_16x16x32_bf16 v[24:27], v[176:179], v[152:155], v[24:27]
	v_mfma_f32_16x16x32_bf16 v[88:91], v[176:179], v[224:227], v[88:91]
	ds_read_b64_tr_b16 v[172:173], v180 offset:224
	ds_read_b64_tr_b16 v[174:175], v180 offset:8672
	ds_read_b64_tr_b16 v[176:177], v180 offset:17120
	ds_read_b64_tr_b16 v[178:179], v180 offset:25568
	s_waitcnt lgkmcnt(4)
	v_mfma_f32_16x16x32_bf16 v[28:31], v[0:3], v[148:151], v[28:31]
	v_mfma_f32_16x16x32_bf16 v[92:95], v[0:3], v[206:209], v[92:95]
	v_mfma_f32_16x16x32_bf16 v[28:31], v[168:171], v[152:155], v[28:31]
	v_mfma_f32_16x16x32_bf16 v[92:95], v[168:171], v[224:227], v[92:95]
	ds_read_b64_tr_b16 v[0:1], v180 offset:256
	ds_read_b64_tr_b16 v[2:3], v180 offset:8704
	ds_read_b64_tr_b16 v[168:169], v180 offset:17152
	ds_read_b64_tr_b16 v[170:171], v180 offset:25600
	s_waitcnt lgkmcnt(4)
	v_mfma_f32_16x16x32_bf16 v[32:35], v[172:175], v[148:151], v[32:35]
	v_mfma_f32_16x16x32_bf16 v[96:99], v[172:175], v[206:209], v[96:99]
	v_mfma_f32_16x16x32_bf16 v[32:35], v[176:179], v[152:155], v[32:35]
	v_mfma_f32_16x16x32_bf16 v[96:99], v[176:179], v[224:227], v[96:99]
	ds_read_b64_tr_b16 v[172:173], v180 offset:288
	ds_read_b64_tr_b16 v[174:175], v180 offset:8736
	ds_read_b64_tr_b16 v[176:177], v180 offset:17184
	ds_read_b64_tr_b16 v[178:179], v180 offset:25632
	s_waitcnt lgkmcnt(4)
	v_mfma_f32_16x16x32_bf16 v[36:39], v[0:3], v[148:151], v[36:39]
	v_mfma_f32_16x16x32_bf16 v[100:103], v[0:3], v[206:209], v[100:103]
	v_mfma_f32_16x16x32_bf16 v[36:39], v[168:171], v[152:155], v[36:39]
	v_mfma_f32_16x16x32_bf16 v[100:103], v[168:171], v[224:227], v[100:103]
	ds_read_b64_tr_b16 v[0:1], v180 offset:320
	ds_read_b64_tr_b16 v[2:3], v180 offset:8768
	ds_read_b64_tr_b16 v[168:169], v180 offset:17216
	ds_read_b64_tr_b16 v[170:171], v180 offset:25664
	s_waitcnt lgkmcnt(4)
	v_mfma_f32_16x16x32_bf16 v[40:43], v[172:175], v[148:151], v[40:43]
	v_mfma_f32_16x16x32_bf16 v[104:107], v[172:175], v[206:209], v[104:107]
	v_mfma_f32_16x16x32_bf16 v[40:43], v[176:179], v[152:155], v[40:43]
	v_mfma_f32_16x16x32_bf16 v[104:107], v[176:179], v[224:227], v[104:107]
	ds_read_b64_tr_b16 v[172:173], v180 offset:352
	ds_read_b64_tr_b16 v[174:175], v180 offset:8800
	ds_read_b64_tr_b16 v[176:177], v180 offset:17248
	ds_read_b64_tr_b16 v[178:179], v180 offset:25696
	s_waitcnt lgkmcnt(4)
	v_mfma_f32_16x16x32_bf16 v[44:47], v[0:3], v[148:151], v[44:47]
	v_mfma_f32_16x16x32_bf16 v[108:111], v[0:3], v[206:209], v[108:111]
	v_mfma_f32_16x16x32_bf16 v[44:47], v[168:171], v[152:155], v[44:47]
	v_mfma_f32_16x16x32_bf16 v[108:111], v[168:171], v[224:227], v[108:111]
	ds_read_b64_tr_b16 v[0:1], v180 offset:384
	ds_read_b64_tr_b16 v[2:3], v180 offset:8832
	ds_read_b64_tr_b16 v[168:169], v180 offset:17280
	ds_read_b64_tr_b16 v[170:171], v180 offset:25728
	s_waitcnt lgkmcnt(4)
	v_mfma_f32_16x16x32_bf16 v[48:51], v[172:175], v[148:151], v[48:51]
	v_mfma_f32_16x16x32_bf16 v[112:115], v[172:175], v[206:209], v[112:115]
	v_mfma_f32_16x16x32_bf16 v[48:51], v[176:179], v[152:155], v[48:51]
	v_mfma_f32_16x16x32_bf16 v[112:115], v[176:179], v[224:227], v[112:115]
	ds_read_b64_tr_b16 v[172:173], v180 offset:416
	ds_read_b64_tr_b16 v[174:175], v180 offset:8864
	ds_read_b64_tr_b16 v[176:177], v180 offset:17312
	ds_read_b64_tr_b16 v[178:179], v180 offset:25760
	s_waitcnt lgkmcnt(4)
	v_mfma_f32_16x16x32_bf16 v[52:55], v[0:3], v[148:151], v[52:55]
	v_mfma_f32_16x16x32_bf16 v[116:119], v[0:3], v[206:209], v[116:119]
	v_mfma_f32_16x16x32_bf16 v[52:55], v[168:171], v[152:155], v[52:55]
	v_mfma_f32_16x16x32_bf16 v[116:119], v[168:171], v[224:227], v[116:119]
	ds_read_b64_tr_b16 v[0:1], v180 offset:448
	ds_read_b64_tr_b16 v[2:3], v180 offset:8896
	ds_read_b64_tr_b16 v[168:169], v180 offset:17344
	ds_read_b64_tr_b16 v[170:171], v180 offset:25792
	s_waitcnt lgkmcnt(4)
	v_mfma_f32_16x16x32_bf16 v[56:59], v[172:175], v[148:151], v[56:59]
	v_mfma_f32_16x16x32_bf16 v[120:123], v[172:175], v[206:209], v[120:123]
	v_mfma_f32_16x16x32_bf16 v[56:59], v[176:179], v[152:155], v[56:59]
	v_mfma_f32_16x16x32_bf16 v[120:123], v[176:179], v[224:227], v[120:123]
	ds_read_b64_tr_b16 v[172:173], v180 offset:480
	ds_read_b64_tr_b16 v[174:175], v180 offset:8928
	ds_read_b64_tr_b16 v[176:177], v180 offset:17376
	ds_read_b64_tr_b16 v[178:179], v180 offset:25824
	s_waitcnt lgkmcnt(4)
	v_mfma_f32_16x16x32_bf16 v[60:63], v[0:3], v[148:151], v[60:63]
	v_mfma_f32_16x16x32_bf16 v[124:127], v[0:3], v[206:209], v[124:127]
	v_mfma_f32_16x16x32_bf16 v[60:63], v[168:171], v[152:155], v[60:63]
	v_mfma_f32_16x16x32_bf16 v[124:127], v[168:171], v[224:227], v[124:127]
	s_waitcnt lgkmcnt(0)
	v_mfma_f32_16x16x32_bf16 v[64:67], v[172:175], v[148:151], v[64:67]
	v_mfma_f32_16x16x32_bf16 v[128:131], v[172:175], v[206:209], v[128:131]
	v_mfma_f32_16x16x32_bf16 v[64:67], v[176:179], v[152:155], v[64:67]
	v_mfma_f32_16x16x32_bf16 v[128:131], v[176:179], v[224:227], v[128:131]
	s_waitcnt vmcnt(0)
	ds_write_b128 v187, v[236:239] offset:33792
	ds_write_b128 v187, v[240:243] offset:33920
	ds_write_b128 v187, v[164:167] offset:34048
	ds_write_b128 v187, v[182:185] offset:34176
	s_waitcnt lgkmcnt(0)
	s_barrier
	ds_read_b64_tr_b16 v[0:1], v180 offset:33792
	ds_read_b64_tr_b16 v[2:3], v180 offset:42240
	ds_read_b64_tr_b16 v[168:169], v180 offset:50688
	ds_read_b64_tr_b16 v[170:171], v180 offset:59136
	ds_read_b64_tr_b16 v[172:173], v180 offset:33824
	ds_read_b64_tr_b16 v[174:175], v180 offset:42272
	ds_read_b64_tr_b16 v[176:177], v180 offset:50720
	ds_read_b64_tr_b16 v[178:179], v180 offset:59168
	s_waitcnt lgkmcnt(4)
	v_mfma_f32_16x16x32_bf16 v[4:7], v[0:3], v[156:159], v[4:7]
	v_mfma_f32_16x16x32_bf16 v[68:71], v[0:3], v[228:231], v[68:71]
	v_mfma_f32_16x16x32_bf16 v[4:7], v[168:171], v[160:163], v[4:7]
	v_mfma_f32_16x16x32_bf16 v[68:71], v[168:171], v[232:235], v[68:71]
	ds_read_b64_tr_b16 v[0:1], v180 offset:33856
	ds_read_b64_tr_b16 v[2:3], v180 offset:42304
	ds_read_b64_tr_b16 v[168:169], v180 offset:50752
	ds_read_b64_tr_b16 v[170:171], v180 offset:59200
	s_waitcnt lgkmcnt(4)
	v_mfma_f32_16x16x32_bf16 v[8:11], v[172:175], v[156:159], v[8:11]
	v_mfma_f32_16x16x32_bf16 v[72:75], v[172:175], v[228:231], v[72:75]
	v_mfma_f32_16x16x32_bf16 v[8:11], v[176:179], v[160:163], v[8:11]
	v_mfma_f32_16x16x32_bf16 v[72:75], v[176:179], v[232:235], v[72:75]
	ds_read_b64_tr_b16 v[172:173], v180 offset:33888
	ds_read_b64_tr_b16 v[174:175], v180 offset:42336
	ds_read_b64_tr_b16 v[176:177], v180 offset:50784
	ds_read_b64_tr_b16 v[178:179], v180 offset:59232
	s_waitcnt lgkmcnt(4)
	v_mfma_f32_16x16x32_bf16 v[12:15], v[0:3], v[156:159], v[12:15]
	v_mfma_f32_16x16x32_bf16 v[76:79], v[0:3], v[228:231], v[76:79]
	v_mfma_f32_16x16x32_bf16 v[12:15], v[168:171], v[160:163], v[12:15]
	v_mfma_f32_16x16x32_bf16 v[76:79], v[168:171], v[232:235], v[76:79]
	ds_read_b64_tr_b16 v[0:1], v180 offset:33920
	ds_read_b64_tr_b16 v[2:3], v180 offset:42368
	ds_read_b64_tr_b16 v[168:169], v180 offset:50816
	ds_read_b64_tr_b16 v[170:171], v180 offset:59264
	s_waitcnt lgkmcnt(4)
	v_mfma_f32_16x16x32_bf16 v[16:19], v[172:175], v[156:159], v[16:19]
	v_mfma_f32_16x16x32_bf16 v[80:83], v[172:175], v[228:231], v[80:83]
	v_mfma_f32_16x16x32_bf16 v[16:19], v[176:179], v[160:163], v[16:19]
	v_mfma_f32_16x16x32_bf16 v[80:83], v[176:179], v[232:235], v[80:83]
	ds_read_b64_tr_b16 v[172:173], v180 offset:33952
	ds_read_b64_tr_b16 v[174:175], v180 offset:42400
	ds_read_b64_tr_b16 v[176:177], v180 offset:50848
	ds_read_b64_tr_b16 v[178:179], v180 offset:59296
	s_waitcnt lgkmcnt(4)
	v_mfma_f32_16x16x32_bf16 v[20:23], v[0:3], v[156:159], v[20:23]
	v_mfma_f32_16x16x32_bf16 v[84:87], v[0:3], v[228:231], v[84:87]
	v_mfma_f32_16x16x32_bf16 v[20:23], v[168:171], v[160:163], v[20:23]
	v_mfma_f32_16x16x32_bf16 v[84:87], v[168:171], v[232:235], v[84:87]
	ds_read_b64_tr_b16 v[0:1], v180 offset:33984
	ds_read_b64_tr_b16 v[2:3], v180 offset:42432
	ds_read_b64_tr_b16 v[168:169], v180 offset:50880
	ds_read_b64_tr_b16 v[170:171], v180 offset:59328
	s_waitcnt lgkmcnt(4)
	v_mfma_f32_16x16x32_bf16 v[24:27], v[172:175], v[156:159], v[24:27]
	v_mfma_f32_16x16x32_bf16 v[88:91], v[172:175], v[228:231], v[88:91]
	v_mfma_f32_16x16x32_bf16 v[24:27], v[176:179], v[160:163], v[24:27]
	v_mfma_f32_16x16x32_bf16 v[88:91], v[176:179], v[232:235], v[88:91]
	ds_read_b64_tr_b16 v[172:173], v180 offset:34016
	ds_read_b64_tr_b16 v[174:175], v180 offset:42464
	ds_read_b64_tr_b16 v[176:177], v180 offset:50912
	ds_read_b64_tr_b16 v[178:179], v180 offset:59360
	s_waitcnt lgkmcnt(4)
	v_mfma_f32_16x16x32_bf16 v[28:31], v[0:3], v[156:159], v[28:31]
	v_mfma_f32_16x16x32_bf16 v[92:95], v[0:3], v[228:231], v[92:95]
	v_mfma_f32_16x16x32_bf16 v[28:31], v[168:171], v[160:163], v[28:31]
	v_mfma_f32_16x16x32_bf16 v[92:95], v[168:171], v[232:235], v[92:95]
	ds_read_b64_tr_b16 v[0:1], v180 offset:34048
	ds_read_b64_tr_b16 v[2:3], v180 offset:42496
	ds_read_b64_tr_b16 v[168:169], v180 offset:50944
	ds_read_b64_tr_b16 v[170:171], v180 offset:59392
	s_waitcnt lgkmcnt(4)
	v_mfma_f32_16x16x32_bf16 v[32:35], v[172:175], v[156:159], v[32:35]
	v_mfma_f32_16x16x32_bf16 v[96:99], v[172:175], v[228:231], v[96:99]
	v_mfma_f32_16x16x32_bf16 v[32:35], v[176:179], v[160:163], v[32:35]
	v_mfma_f32_16x16x32_bf16 v[96:99], v[176:179], v[232:235], v[96:99]
	ds_read_b64_tr_b16 v[172:173], v180 offset:34080
	ds_read_b64_tr_b16 v[174:175], v180 offset:42528
	ds_read_b64_tr_b16 v[176:177], v180 offset:50976
	ds_read_b64_tr_b16 v[178:179], v180 offset:59424
	s_waitcnt lgkmcnt(4)
	v_mfma_f32_16x16x32_bf16 v[36:39], v[0:3], v[156:159], v[36:39]
	v_mfma_f32_16x16x32_bf16 v[100:103], v[0:3], v[228:231], v[100:103]
	v_mfma_f32_16x16x32_bf16 v[36:39], v[168:171], v[160:163], v[36:39]
	v_mfma_f32_16x16x32_bf16 v[100:103], v[168:171], v[232:235], v[100:103]
	ds_read_b64_tr_b16 v[0:1], v180 offset:34112
	ds_read_b64_tr_b16 v[2:3], v180 offset:42560
	ds_read_b64_tr_b16 v[168:169], v180 offset:51008
	ds_read_b64_tr_b16 v[170:171], v180 offset:59456
	s_waitcnt lgkmcnt(4)
	v_mfma_f32_16x16x32_bf16 v[40:43], v[172:175], v[156:159], v[40:43]
	v_mfma_f32_16x16x32_bf16 v[104:107], v[172:175], v[228:231], v[104:107]
	v_mfma_f32_16x16x32_bf16 v[40:43], v[176:179], v[160:163], v[40:43]
	v_mfma_f32_16x16x32_bf16 v[104:107], v[176:179], v[232:235], v[104:107]
	ds_read_b64_tr_b16 v[172:173], v180 offset:34144
	ds_read_b64_tr_b16 v[174:175], v180 offset:42592
	ds_read_b64_tr_b16 v[176:177], v180 offset:51040
	ds_read_b64_tr_b16 v[178:179], v180 offset:59488
	s_waitcnt lgkmcnt(4)
	v_mfma_f32_16x16x32_bf16 v[44:47], v[0:3], v[156:159], v[44:47]
	v_mfma_f32_16x16x32_bf16 v[108:111], v[0:3], v[228:231], v[108:111]
	v_mfma_f32_16x16x32_bf16 v[44:47], v[168:171], v[160:163], v[44:47]
	v_mfma_f32_16x16x32_bf16 v[108:111], v[168:171], v[232:235], v[108:111]
	ds_read_b64_tr_b16 v[0:1], v180 offset:34176
	ds_read_b64_tr_b16 v[2:3], v180 offset:42624
	ds_read_b64_tr_b16 v[168:169], v180 offset:51072
	ds_read_b64_tr_b16 v[170:171], v180 offset:59520
	s_waitcnt lgkmcnt(4)
	v_mfma_f32_16x16x32_bf16 v[48:51], v[172:175], v[156:159], v[48:51]
	v_mfma_f32_16x16x32_bf16 v[112:115], v[172:175], v[228:231], v[112:115]
	v_mfma_f32_16x16x32_bf16 v[48:51], v[176:179], v[160:163], v[48:51]
	v_mfma_f32_16x16x32_bf16 v[112:115], v[176:179], v[232:235], v[112:115]
	ds_read_b64_tr_b16 v[172:173], v180 offset:34208
	ds_read_b64_tr_b16 v[174:175], v180 offset:42656
	ds_read_b64_tr_b16 v[176:177], v180 offset:51104
	ds_read_b64_tr_b16 v[178:179], v180 offset:59552
	s_waitcnt lgkmcnt(4)
	v_mfma_f32_16x16x32_bf16 v[52:55], v[0:3], v[156:159], v[52:55]
	v_mfma_f32_16x16x32_bf16 v[116:119], v[0:3], v[228:231], v[116:119]
	v_mfma_f32_16x16x32_bf16 v[52:55], v[168:171], v[160:163], v[52:55]
	v_mfma_f32_16x16x32_bf16 v[116:119], v[168:171], v[232:235], v[116:119]
	ds_read_b64_tr_b16 v[0:1], v180 offset:34240
	ds_read_b64_tr_b16 v[2:3], v180 offset:42688
	ds_read_b64_tr_b16 v[168:169], v180 offset:51136
	ds_read_b64_tr_b16 v[170:171], v180 offset:59584
	s_waitcnt lgkmcnt(4)
	v_mfma_f32_16x16x32_bf16 v[56:59], v[172:175], v[156:159], v[56:59]
	v_mfma_f32_16x16x32_bf16 v[120:123], v[172:175], v[228:231], v[120:123]
	v_mfma_f32_16x16x32_bf16 v[56:59], v[176:179], v[160:163], v[56:59]
	v_mfma_f32_16x16x32_bf16 v[120:123], v[176:179], v[232:235], v[120:123]
	ds_read_b64_tr_b16 v[172:173], v180 offset:34272
	ds_read_b64_tr_b16 v[174:175], v180 offset:42720
	ds_read_b64_tr_b16 v[176:177], v180 offset:51168
	ds_read_b64_tr_b16 v[178:179], v180 offset:59616
	s_waitcnt lgkmcnt(4)
	v_mfma_f32_16x16x32_bf16 v[60:63], v[0:3], v[156:159], v[60:63]
	v_mfma_f32_16x16x32_bf16 v[124:127], v[0:3], v[228:231], v[124:127]
	v_mfma_f32_16x16x32_bf16 v[60:63], v[168:171], v[160:163], v[60:63]
	v_mfma_f32_16x16x32_bf16 v[124:127], v[168:171], v[232:235], v[124:127]
	s_waitcnt lgkmcnt(0)
	v_mfma_f32_16x16x32_bf16 v[64:67], v[172:175], v[156:159], v[64:67]
	v_mfma_f32_16x16x32_bf16 v[128:131], v[172:175], v[228:231], v[128:131]
	v_mfma_f32_16x16x32_bf16 v[64:67], v[176:179], v[160:163], v[64:67]
	v_mfma_f32_16x16x32_bf16 v[128:131], v[176:179], v[232:235], v[128:131]
	s_nop 7
	s_nop 1
	v_lshrrev_b32_e32 v176, 6, v217
	v_and_b32_e32 v177, 15, v217
	v_lshl_add_u32 v176, v176, 4, v177
	v_mul_u32_u24_e32 v176, 0x210, v176
	v_bfe_u32 v177, v217, 4, 2
	v_lshl_add_u32 v176, v177, 3, v176
	v_lshrrev_b32_e32 v177, 6, v217
	v_lshlrev_b32_e32 v177, 4, v177
	v_bfe_u32 v178, v217, 5, 1
	v_add_u32_e32 v179, v177, v178
	v_mul_u32_u24_e32 v177, 0x210, v179
	v_and_b32_e32 v178, 31, v217
	v_lshlrev_b32_e32 v178, 4, v178
	v_add_u32_e32 v177, v177, v178
	v_add_u32_e32 v218, s14, v179
	v_mov_b32_e32 v219, 0
	v_lshlrev_b64 v[172:173], 11, v[218:219]
	v_readlane_b32 s12, v253, 35
	v_readlane_b32 s13, v253, 36
	s_add_u32 s10, s12, s10
	s_addc_u32 s11, s13, s11
	v_lshl_add_u64 v[172:173], s[10:11], 0, v[172:173]
	v_mov_b32_e32 v179, 0xa00000
	v_mad_i64_i32 v[172:173], s[12:13], s6, v179, v[172:173]
	v_lshl_add_u64 v[172:173], v[172:173], 0, s[8:9]
	v_mov_b32_e32 v218, v178
	v_lshl_add_u64 v[172:173], v[172:173], 0, v[218:219]
	v_mov_b32_e32 v218, 0x40000
	v_lshl_add_u64 v[174:175], v[172:173], 0, v[218:219]
	v_mov_b32_e32 v218, 0x1000
	v_div_scale_f32 v0, s[12:13], v220, v220, 1.0
	v_rcp_f32_e32 v1, v0
	s_nop 0
	v_fma_f32 v2, -v0, v1, 1.0
	v_fmac_f32_e32 v1, v2, v1
	v_div_scale_f32 v2, vcc, 1.0, v220, 1.0
	v_mul_f32_e32 v3, v2, v1
	v_fma_f32 v168, -v0, v3, v2
	v_fmac_f32_e32 v3, v168, v1
	v_fma_f32 v0, -v0, v3, v2
	v_div_fmas_f32 v0, v0, v1, v3
	v_div_fixup_f32 v178, v0, v220, 1.0
	v_div_scale_f32 v0, s[12:13], v221, v221, 1.0
	v_rcp_f32_e32 v1, v0
	s_nop 0
	v_fma_f32 v2, -v0, v1, 1.0
	v_fmac_f32_e32 v1, v2, v1
	v_div_scale_f32 v2, vcc, 1.0, v221, 1.0
	v_mul_f32_e32 v3, v2, v1
	v_fma_f32 v168, -v0, v3, v2
	v_fmac_f32_e32 v3, v168, v1
	v_fma_f32 v0, -v0, v3, v2
	v_div_fmas_f32 v0, v0, v1, v3
	v_div_fixup_f32 v179, v0, v221, 1.0
	v_mul_f32_e32 v4, v178, v4
	v_mul_f32_e32 v5, v178, v5
	v_mul_f32_e32 v6, v178, v6
	v_mul_f32_e32 v7, v178, v7
	v_cvt_pk_bf16_f32 v236, v4, v5
	v_cvt_pk_bf16_f32 v237, v6, v7
	ds_write_b64 v176, v[236:237]
	v_mul_f32_e32 v8, v178, v8
	v_mul_f32_e32 v9, v178, v9
	v_mul_f32_e32 v10, v178, v10
	v_mul_f32_e32 v11, v178, v11
	v_cvt_pk_bf16_f32 v238, v8, v9
	v_cvt_pk_bf16_f32 v239, v10, v11
	ds_write_b64 v176, v[238:239] offset:32
	v_mul_f32_e32 v12, v178, v12
	v_mul_f32_e32 v13, v178, v13
	v_mul_f32_e32 v14, v178, v14
	v_mul_f32_e32 v15, v178, v15
	v_cvt_pk_bf16_f32 v240, v12, v13
	v_cvt_pk_bf16_f32 v241, v14, v15
	ds_write_b64 v176, v[240:241] offset:64
	v_mul_f32_e32 v16, v178, v16
	v_mul_f32_e32 v17, v178, v17
	v_mul_f32_e32 v18, v178, v18
	v_mul_f32_e32 v19, v178, v19
	v_cvt_pk_bf16_f32 v242, v16, v17
	v_cvt_pk_bf16_f32 v243, v18, v19
	ds_write_b64 v176, v[242:243] offset:96
	v_mul_f32_e32 v20, v178, v20
	v_mul_f32_e32 v21, v178, v21
	v_mul_f32_e32 v22, v178, v22
	v_mul_f32_e32 v23, v178, v23
	v_cvt_pk_bf16_f32 v164, v20, v21
	v_cvt_pk_bf16_f32 v165, v22, v23
	ds_write_b64 v176, v[164:165] offset:128
	v_mul_f32_e32 v24, v178, v24
	v_mul_f32_e32 v25, v178, v25
	v_mul_f32_e32 v26, v178, v26
	v_mul_f32_e32 v27, v178, v27
	v_cvt_pk_bf16_f32 v166, v24, v25
	v_cvt_pk_bf16_f32 v167, v26, v27
	ds_write_b64 v176, v[166:167] offset:160
	v_mul_f32_e32 v28, v178, v28
	v_mul_f32_e32 v29, v178, v29
	v_mul_f32_e32 v30, v178, v30
	v_mul_f32_e32 v31, v178, v31
	v_cvt_pk_bf16_f32 v182, v28, v29
	v_cvt_pk_bf16_f32 v183, v30, v31
	ds_write_b64 v176, v[182:183] offset:192
	v_mul_f32_e32 v32, v178, v32
	v_mul_f32_e32 v33, v178, v33
	v_mul_f32_e32 v34, v178, v34
	v_mul_f32_e32 v35, v178, v35
	v_cvt_pk_bf16_f32 v184, v32, v33
	v_cvt_pk_bf16_f32 v185, v34, v35
	ds_write_b64 v176, v[184:185] offset:224
	v_mul_f32_e32 v36, v178, v36
	v_mul_f32_e32 v37, v178, v37
	v_mul_f32_e32 v38, v178, v38
	v_mul_f32_e32 v39, v178, v39
	v_cvt_pk_bf16_f32 v236, v36, v37
	v_cvt_pk_bf16_f32 v237, v38, v39
	ds_write_b64 v176, v[236:237] offset:256
	v_mul_f32_e32 v40, v178, v40
	v_mul_f32_e32 v41, v178, v41
	v_mul_f32_e32 v42, v178, v42
	v_mul_f32_e32 v43, v178, v43
	v_cvt_pk_bf16_f32 v238, v40, v41
	v_cvt_pk_bf16_f32 v239, v42, v43
	ds_write_b64 v176, v[238:239] offset:288
	v_mul_f32_e32 v44, v178, v44
	v_mul_f32_e32 v45, v178, v45
	v_mul_f32_e32 v46, v178, v46
	v_mul_f32_e32 v47, v178, v47
	v_cvt_pk_bf16_f32 v240, v44, v45
	v_cvt_pk_bf16_f32 v241, v46, v47
	ds_write_b64 v176, v[240:241] offset:320
	v_mul_f32_e32 v48, v178, v48
	v_mul_f32_e32 v49, v178, v49
	v_mul_f32_e32 v50, v178, v50
	v_mul_f32_e32 v51, v178, v51
	v_cvt_pk_bf16_f32 v242, v48, v49
	v_cvt_pk_bf16_f32 v243, v50, v51
	ds_write_b64 v176, v[242:243] offset:352
	v_mul_f32_e32 v52, v178, v52
	v_mul_f32_e32 v53, v178, v53
	v_mul_f32_e32 v54, v178, v54
	v_mul_f32_e32 v55, v178, v55
	v_cvt_pk_bf16_f32 v164, v52, v53
	v_cvt_pk_bf16_f32 v165, v54, v55
	ds_write_b64 v176, v[164:165] offset:384
	v_mul_f32_e32 v56, v178, v56
	v_mul_f32_e32 v57, v178, v57
	v_mul_f32_e32 v58, v178, v58
	v_mul_f32_e32 v59, v178, v59
	v_cvt_pk_bf16_f32 v166, v56, v57
	v_cvt_pk_bf16_f32 v167, v58, v59
	ds_write_b64 v176, v[166:167] offset:416
	v_mul_f32_e32 v60, v178, v60
	v_mul_f32_e32 v61, v178, v61
	v_mul_f32_e32 v62, v178, v62
	v_mul_f32_e32 v63, v178, v63
	v_cvt_pk_bf16_f32 v182, v60, v61
	v_cvt_pk_bf16_f32 v183, v62, v63
	ds_write_b64 v176, v[182:183] offset:448
	v_mul_f32_e32 v64, v178, v64
	v_mul_f32_e32 v65, v178, v65
	v_mul_f32_e32 v66, v178, v66
	v_mul_f32_e32 v67, v178, v67
	v_cvt_pk_bf16_f32 v184, v64, v65
	v_cvt_pk_bf16_f32 v185, v66, v67
	ds_write_b64 v176, v[184:185] offset:480
	s_waitcnt lgkmcnt(0)
	ds_read_b128 v[132:135], v177
	ds_read_b128 v[136:139], v177 offset:1056
	ds_read_b128 v[140:143], v177 offset:2112
	ds_read_b128 v[144:147], v177 offset:3168
	ds_read_b128 v[148:151], v177 offset:4224
	ds_read_b128 v[152:155], v177 offset:5280
	ds_read_b128 v[156:159], v177 offset:6336
	ds_read_b128 v[160:163], v177 offset:7392
	s_waitcnt lgkmcnt(7)
	global_store_dwordx4 v[172:173], v[132:135], off
	v_lshl_add_u64 v[172:173], v[172:173], 0, v[218:219]
	s_waitcnt lgkmcnt(6)
	global_store_dwordx4 v[172:173], v[136:139], off
	v_lshl_add_u64 v[172:173], v[172:173], 0, v[218:219]
	s_waitcnt lgkmcnt(5)
	global_store_dwordx4 v[172:173], v[140:143], off
	v_lshl_add_u64 v[172:173], v[172:173], 0, v[218:219]
	s_waitcnt lgkmcnt(4)
	global_store_dwordx4 v[172:173], v[144:147], off
	v_lshl_add_u64 v[172:173], v[172:173], 0, v[218:219]
	s_waitcnt lgkmcnt(3)
	global_store_dwordx4 v[172:173], v[148:151], off
	v_lshl_add_u64 v[172:173], v[172:173], 0, v[218:219]
	s_waitcnt lgkmcnt(2)
	global_store_dwordx4 v[172:173], v[152:155], off
	v_lshl_add_u64 v[172:173], v[172:173], 0, v[218:219]
	s_waitcnt lgkmcnt(1)
	global_store_dwordx4 v[172:173], v[156:159], off
	v_lshl_add_u64 v[172:173], v[172:173], 0, v[218:219]
	s_waitcnt lgkmcnt(0)
	global_store_dwordx4 v[172:173], v[160:163], off
	v_mul_f32_e32 v68, v179, v68
	v_mul_f32_e32 v69, v179, v69
	v_mul_f32_e32 v70, v179, v70
	v_mul_f32_e32 v71, v179, v71
	v_cvt_pk_bf16_f32 v236, v68, v69
	v_cvt_pk_bf16_f32 v237, v70, v71
	ds_write_b64 v176, v[236:237]
	v_mul_f32_e32 v72, v179, v72
	v_mul_f32_e32 v73, v179, v73
	v_mul_f32_e32 v74, v179, v74
	v_mul_f32_e32 v75, v179, v75
	v_cvt_pk_bf16_f32 v238, v72, v73
	v_cvt_pk_bf16_f32 v239, v74, v75
	ds_write_b64 v176, v[238:239] offset:32
	v_mul_f32_e32 v76, v179, v76
	v_mul_f32_e32 v77, v179, v77
	v_mul_f32_e32 v78, v179, v78
	v_mul_f32_e32 v79, v179, v79
	v_cvt_pk_bf16_f32 v240, v76, v77
	v_cvt_pk_bf16_f32 v241, v78, v79
	ds_write_b64 v176, v[240:241] offset:64
	v_mul_f32_e32 v80, v179, v80
	v_mul_f32_e32 v81, v179, v81
	v_mul_f32_e32 v82, v179, v82
	v_mul_f32_e32 v83, v179, v83
	v_cvt_pk_bf16_f32 v242, v80, v81
	v_cvt_pk_bf16_f32 v243, v82, v83
	ds_write_b64 v176, v[242:243] offset:96
	v_mul_f32_e32 v84, v179, v84
	v_mul_f32_e32 v85, v179, v85
	v_mul_f32_e32 v86, v179, v86
	v_mul_f32_e32 v87, v179, v87
	v_cvt_pk_bf16_f32 v164, v84, v85
	v_cvt_pk_bf16_f32 v165, v86, v87
	ds_write_b64 v176, v[164:165] offset:128
	v_mul_f32_e32 v88, v179, v88
	v_mul_f32_e32 v89, v179, v89
	v_mul_f32_e32 v90, v179, v90
	v_mul_f32_e32 v91, v179, v91
	v_cvt_pk_bf16_f32 v166, v88, v89
	v_cvt_pk_bf16_f32 v167, v90, v91
	ds_write_b64 v176, v[166:167] offset:160
	v_mul_f32_e32 v92, v179, v92
	v_mul_f32_e32 v93, v179, v93
	v_mul_f32_e32 v94, v179, v94
	v_mul_f32_e32 v95, v179, v95
	v_cvt_pk_bf16_f32 v182, v92, v93
	v_cvt_pk_bf16_f32 v183, v94, v95
	ds_write_b64 v176, v[182:183] offset:192
	v_mul_f32_e32 v96, v179, v96
	v_mul_f32_e32 v97, v179, v97
	v_mul_f32_e32 v98, v179, v98
	v_mul_f32_e32 v99, v179, v99
	v_cvt_pk_bf16_f32 v184, v96, v97
	v_cvt_pk_bf16_f32 v185, v98, v99
	ds_write_b64 v176, v[184:185] offset:224
	v_mul_f32_e32 v100, v179, v100
	v_mul_f32_e32 v101, v179, v101
	v_mul_f32_e32 v102, v179, v102
	v_mul_f32_e32 v103, v179, v103
	v_cvt_pk_bf16_f32 v236, v100, v101
	v_cvt_pk_bf16_f32 v237, v102, v103
	ds_write_b64 v176, v[236:237] offset:256
	v_mul_f32_e32 v104, v179, v104
	v_mul_f32_e32 v105, v179, v105
	v_mul_f32_e32 v106, v179, v106
	v_mul_f32_e32 v107, v179, v107
	v_cvt_pk_bf16_f32 v238, v104, v105
	v_cvt_pk_bf16_f32 v239, v106, v107
	ds_write_b64 v176, v[238:239] offset:288
	v_mul_f32_e32 v108, v179, v108
	v_mul_f32_e32 v109, v179, v109
	v_mul_f32_e32 v110, v179, v110
	v_mul_f32_e32 v111, v179, v111
	v_cvt_pk_bf16_f32 v240, v108, v109
	v_cvt_pk_bf16_f32 v241, v110, v111
	ds_write_b64 v176, v[240:241] offset:320
	v_mul_f32_e32 v112, v179, v112
	v_mul_f32_e32 v113, v179, v113
	v_mul_f32_e32 v114, v179, v114
	v_mul_f32_e32 v115, v179, v115
	v_cvt_pk_bf16_f32 v242, v112, v113
	v_cvt_pk_bf16_f32 v243, v114, v115
	ds_write_b64 v176, v[242:243] offset:352
	v_mul_f32_e32 v116, v179, v116
	v_mul_f32_e32 v117, v179, v117
	v_mul_f32_e32 v118, v179, v118
	v_mul_f32_e32 v119, v179, v119
	v_cvt_pk_bf16_f32 v164, v116, v117
	v_cvt_pk_bf16_f32 v165, v118, v119
	ds_write_b64 v176, v[164:165] offset:384
	v_mul_f32_e32 v120, v179, v120
	v_mul_f32_e32 v121, v179, v121
	v_mul_f32_e32 v122, v179, v122
	v_mul_f32_e32 v123, v179, v123
	v_cvt_pk_bf16_f32 v166, v120, v121
	v_cvt_pk_bf16_f32 v167, v122, v123
	ds_write_b64 v176, v[166:167] offset:416
	v_mul_f32_e32 v124, v179, v124
	v_mul_f32_e32 v125, v179, v125
	v_mul_f32_e32 v126, v179, v126
	v_mul_f32_e32 v127, v179, v127
	v_cvt_pk_bf16_f32 v182, v124, v125
	v_cvt_pk_bf16_f32 v183, v126, v127
	ds_write_b64 v176, v[182:183] offset:448
	v_mul_f32_e32 v128, v179, v128
	v_mul_f32_e32 v129, v179, v129
	v_mul_f32_e32 v130, v179, v130
	v_mul_f32_e32 v131, v179, v131
	v_cvt_pk_bf16_f32 v184, v128, v129
	v_cvt_pk_bf16_f32 v185, v130, v131
	ds_write_b64 v176, v[184:185] offset:480
	s_waitcnt lgkmcnt(0)
	ds_read_b128 v[190:193], v177
	ds_read_b128 v[194:197], v177 offset:1056
	ds_read_b128 v[198:201], v177 offset:2112
	ds_read_b128 v[202:205], v177 offset:3168
	ds_read_b128 v[206:209], v177 offset:4224
	ds_read_b128 v[224:227], v177 offset:5280
	ds_read_b128 v[228:231], v177 offset:6336
	ds_read_b128 v[232:235], v177 offset:7392
	s_waitcnt lgkmcnt(7)
	global_store_dwordx4 v[174:175], v[190:193], off
	v_lshl_add_u64 v[174:175], v[174:175], 0, v[218:219]
	s_waitcnt lgkmcnt(6)
	global_store_dwordx4 v[174:175], v[194:197], off
	v_lshl_add_u64 v[174:175], v[174:175], 0, v[218:219]
	s_waitcnt lgkmcnt(5)
	global_store_dwordx4 v[174:175], v[198:201], off
	v_lshl_add_u64 v[174:175], v[174:175], 0, v[218:219]
	s_waitcnt lgkmcnt(4)
	global_store_dwordx4 v[174:175], v[202:205], off
	v_lshl_add_u64 v[174:175], v[174:175], 0, v[218:219]
	s_waitcnt lgkmcnt(3)
	global_store_dwordx4 v[174:175], v[206:209], off
	v_lshl_add_u64 v[174:175], v[174:175], 0, v[218:219]
	s_waitcnt lgkmcnt(2)
	global_store_dwordx4 v[174:175], v[224:227], off
	v_lshl_add_u64 v[174:175], v[174:175], 0, v[218:219]
	s_waitcnt lgkmcnt(1)
	global_store_dwordx4 v[174:175], v[228:231], off
	v_lshl_add_u64 v[174:175], v[174:175], 0, v[218:219]
	s_waitcnt lgkmcnt(0)
	global_store_dwordx4 v[174:175], v[232:235], off
	v_mov_b32_e32 v2, 0x3f803f80
	s_waitcnt lgkmcnt(0)
	s_barrier
